# lever 7: ssq cross-lane reductions in the down/out GEMM epilogues use v_permlane16_swap / v_permlane32_swap on a register copy instead of ds_bpermute + lgkmcnt round trips
# baseline (speedup 1.0000x reference)
.LBB0_284:
	v_lshl_add_u32 v184, s8, 8, v209
	v_lshl_or_b32 v182, s83, 8, v211
	v_ashrrev_i32_e32 v185, 31, v184
	s_andn2_b64 vcc, exec, s[20:21]
	v_ashrrev_i32_e32 v183, 31, v182
	s_cbranch_vccnz .LBB0_303
	v_or_b32_e32 v198, 0, v184
	v_ashrrev_i32_e32 v199, 31, v198
	v_lshlrev_b64 v[198:199], 10, v[198:199]
	v_lshl_add_u64 v[198:199], v[198:199], 0, v[182:183]
	v_lshl_add_u64 v[198:199], v[198:199], 2, s[16:17]
	global_load_dwordx4 v[148:151], v[198:199], off offset:16
	global_load_dwordx4 v[186:189], v[198:199], off
	global_load_dwordx4 v[190:193], v[198:199], off offset:528
	global_load_dwordx4 v[194:197], v[198:199], off offset:512
	v_or_b32_e32 v198, 16, v184
	v_ashrrev_i32_e32 v199, 31, v198
	v_lshlrev_b64 v[198:199], 10, v[198:199]
	v_lshl_add_u64 v[198:199], v[198:199], 0, v[182:183]
	v_lshl_add_u64 v[198:199], v[198:199], 2, s[16:17]
	global_load_dwordx4 v[214:217], v[198:199], off offset:16
	global_load_dwordx4 v[218:221], v[198:199], off
	global_load_dwordx4 v[224:227], v[198:199], off offset:528
	global_load_dwordx4 v[228:231], v[198:199], off offset:512
	v_or_b32_e32 v198, 32, v184
	v_ashrrev_i32_e32 v199, 31, v198
	v_lshlrev_b64 v[198:199], 10, v[198:199]
	v_lshl_add_u64 v[198:199], v[198:199], 0, v[182:183]
	v_lshl_add_u64 v[198:199], v[198:199], 2, s[16:17]
	global_load_dwordx4 v[232:235], v[198:199], off offset:16
	global_load_dwordx4 v[236:239], v[198:199], off
	v_lshlrev_b64 v[128:129], 10, v[184:185]
	v_lshl_add_u64 v[136:137], v[128:129], 0, v[182:183]
	v_lshl_add_u64 v[138:139], v[136:137], 2, s[16:17]
	v_lshl_add_u64 v[136:137], v[136:137], 1, s[26:27]
	s_lshl_b32 s60, s83, 2
	s_ashr_i32 s61, s60, 31
	s_waitcnt vmcnt(6)
	v_pk_fma_f32 v[142:143], v[120:121], 0.5, v[148:149] op_sel_hi:[1,0,1]
	v_pk_fma_f32 v[134:135], v[126:127], 0.5, v[188:189] op_sel_hi:[1,0,1]
	v_pk_fma_f32 v[132:133], v[124:125], 0.5, v[186:187] op_sel_hi:[1,0,1]
	v_pk_fma_f32 v[140:141], v[122:123], 0.5, v[150:151] op_sel_hi:[1,0,1]
	v_cvt_pk_bf16_f32 v128, v132, v133
	v_cvt_pk_bf16_f32 v129, v134, v135
	v_cvt_pk_bf16_f32 v130, v142, v143
	s_nop 0
	v_cvt_pk_bf16_f32 v131, v140, v141
	global_store_dwordx4 v[136:137], v[128:131], off
	s_nop 1
	v_mul_f32_e32 v128, v133, v133
	v_mul_f32_e32 v129, v135, v135
	v_fmac_f32_e32 v128, v132, v132
	v_fmac_f32_e32 v129, v134, v134
	v_add_f32_e32 v128, v128, v129
	v_mul_f32_e32 v129, v143, v143
	v_fmac_f32_e32 v129, v142, v142
	v_add_f32_e32 v128, v129, v128
	v_mul_f32_e32 v129, v141, v141
	v_fmac_f32_e32 v129, v140, v140
	v_add_f32_e32 v142, v129, v128
	v_pk_fma_f32 v[140:141], v[112:113], 0.5, v[190:191] op_sel_hi:[1,0,1]
	v_pk_fma_f32 v[134:135], v[118:119], 0.5, v[196:197] op_sel_hi:[1,0,1]
	v_pk_fma_f32 v[132:133], v[116:117], 0.5, v[194:195] op_sel_hi:[1,0,1]
	v_pk_fma_f32 v[138:139], v[114:115], 0.5, v[192:193] op_sel_hi:[1,0,1]
	v_cvt_pk_bf16_f32 v128, v132, v133
	v_cvt_pk_bf16_f32 v129, v134, v135
	v_cvt_pk_bf16_f32 v130, v140, v141
	s_nop 0
	v_cvt_pk_bf16_f32 v131, v138, v139
	global_store_dwordx4 v[136:137], v[128:131], off offset:256
	s_nop 1
	v_mul_f32_e32 v128, v133, v133
	v_mul_f32_e32 v129, v135, v135
	v_fmac_f32_e32 v128, v132, v132
	v_fmac_f32_e32 v129, v134, v134
	v_add_f32_e32 v128, v128, v129
	v_mul_f32_e32 v129, v141, v141
	v_fmac_f32_e32 v129, v140, v140
	v_add_f32_e32 v128, v129, v128
	v_mul_f32_e32 v129, v139, v139
	v_fmac_f32_e32 v129, v138, v138
	v_add_f32_e32 v128, v129, v128
	v_xor_b32_e32 v129, 16, v204
	v_cmp_lt_i32_e32 vcc, v129, v205
	v_add_f32_e32 v128, v142, v128
	s_nop 0
	v_cndmask_b32_e32 v129, v204, v129, vcc
	v_lshlrev_b32_e32 v130, 2, v129
	v_mov_b32_e32 v129, v128
	s_nop 1
	v_permlane16_swap_b32 v128, v129
	s_waitcnt lgkmcnt(0)
	v_add_f32_e32 v128, v128, v129
	v_xor_b32_e32 v129, 32, v204
	v_cmp_lt_i32_e32 vcc, v129, v205
	s_nop 1
	v_cndmask_b32_e32 v129, v204, v129, vcc
	v_lshlrev_b32_e32 v131, 2, v129
	v_mov_b32_e32 v129, v128
	s_nop 1
	v_permlane32_swap_b32 v128, v129
	s_and_saveexec_b64 s[18:19], s[46:47]
	s_cbranch_execz .LBB0_287
	v_lshlrev_b64 v[132:133], 6, v[184:185]
	v_lshl_add_u64 v[132:133], s[28:29], 0, v[132:133]
	v_lshl_add_u64 v[132:133], s[60:61], 2, v[132:133]
	s_lshl_b32 s8, s78, 2
	v_lshl_add_u64 v[132:133], v[132:133], 0, s[8:9]
	s_waitcnt lgkmcnt(0)
	v_add_f32_e32 v128, v128, v129
	flat_store_dword v[132:133], v128
.LBB0_287:
	s_or_b64 exec, exec, s[18:19]
	v_or_b32_e32 v198, 32, v184
	v_ashrrev_i32_e32 v199, 31, v198
	v_lshlrev_b64 v[198:199], 10, v[198:199]
	v_lshl_add_u64 v[198:199], v[198:199], 0, v[182:183]
	v_lshl_add_u64 v[198:199], v[198:199], 2, s[16:17]
	global_load_dwordx4 v[112:115], v[198:199], off offset:528
	global_load_dwordx4 v[116:119], v[198:199], off offset:512
	v_or_b32_e32 v198, 48, v184
	v_ashrrev_i32_e32 v199, 31, v198
	v_lshlrev_b64 v[198:199], 10, v[198:199]
	v_lshl_add_u64 v[198:199], v[198:199], 0, v[182:183]
	v_lshl_add_u64 v[198:199], v[198:199], 2, s[16:17]
	global_load_dwordx4 v[120:123], v[198:199], off offset:16
	global_load_dwordx4 v[124:127], v[198:199], off
	global_load_dwordx4 v[148:151], v[198:199], off offset:528
	global_load_dwordx4 v[186:189], v[198:199], off offset:512
	v_add_u32_e32 v198, 128, v184
	v_ashrrev_i32_e32 v199, 31, v198
	v_lshlrev_b64 v[198:199], 10, v[198:199]
	v_lshl_add_u64 v[198:199], v[198:199], 0, v[182:183]
	v_lshl_add_u64 v[198:199], v[198:199], 2, s[16:17]
	global_load_dwordx4 v[190:193], v[198:199], off offset:16
	global_load_dwordx4 v[194:197], v[198:199], off
	v_or_b32_e32 v128, 16, v184
	s_waitcnt lgkmcnt(0)
	v_ashrrev_i32_e32 v129, 31, v128
	v_lshlrev_b64 v[132:133], 10, v[128:129]
	v_lshl_add_u64 v[140:141], v[132:133], 0, v[182:183]
	v_lshl_add_u64 v[142:143], v[140:141], 2, s[16:17]
	v_lshl_add_u64 v[140:141], v[140:141], 1, s[26:27]
	s_waitcnt vmcnt(13)
	v_pk_fma_f32 v[146:147], v[104:105], 0.5, v[214:215] op_sel_hi:[1,0,1]
	v_pk_fma_f32 v[138:139], v[110:111], 0.5, v[220:221] op_sel_hi:[1,0,1]
	v_pk_fma_f32 v[136:137], v[108:109], 0.5, v[218:219] op_sel_hi:[1,0,1]
	v_pk_fma_f32 v[144:145], v[106:107], 0.5, v[216:217] op_sel_hi:[1,0,1]
	v_cvt_pk_bf16_f32 v132, v136, v137
	v_cvt_pk_bf16_f32 v133, v138, v139
	v_cvt_pk_bf16_f32 v134, v146, v147
	s_nop 0
	v_cvt_pk_bf16_f32 v135, v144, v145
	global_store_dwordx4 v[140:141], v[132:135], off
	s_nop 1
	v_mul_f32_e32 v132, v137, v137
	v_mul_f32_e32 v133, v139, v139
	v_fmac_f32_e32 v132, v136, v136
	v_fmac_f32_e32 v133, v138, v138
	v_add_f32_e32 v132, v132, v133
	v_mul_f32_e32 v133, v147, v147
	v_fmac_f32_e32 v133, v146, v146
	v_add_f32_e32 v132, v133, v132
	v_mul_f32_e32 v133, v145, v145
	v_fmac_f32_e32 v133, v144, v144
	v_add_f32_e32 v146, v133, v132
	v_pk_fma_f32 v[144:145], v[96:97], 0.5, v[224:225] op_sel_hi:[1,0,1]
	v_pk_fma_f32 v[138:139], v[102:103], 0.5, v[230:231] op_sel_hi:[1,0,1]
	v_pk_fma_f32 v[136:137], v[100:101], 0.5, v[228:229] op_sel_hi:[1,0,1]
	v_pk_fma_f32 v[142:143], v[98:99], 0.5, v[226:227] op_sel_hi:[1,0,1]
	v_cvt_pk_bf16_f32 v132, v136, v137
	v_cvt_pk_bf16_f32 v133, v138, v139
	v_cvt_pk_bf16_f32 v134, v144, v145
	s_nop 0
	v_cvt_pk_bf16_f32 v135, v142, v143
	global_store_dwordx4 v[140:141], v[132:135], off offset:256
	s_nop 1
	v_mul_f32_e32 v132, v137, v137
	v_mul_f32_e32 v133, v139, v139
	v_fmac_f32_e32 v132, v136, v136
	v_fmac_f32_e32 v133, v138, v138
	v_add_f32_e32 v132, v132, v133
	v_mul_f32_e32 v133, v145, v145
	v_fmac_f32_e32 v133, v144, v144
	v_add_f32_e32 v132, v133, v132
	v_mul_f32_e32 v133, v143, v143
	v_fmac_f32_e32 v133, v142, v142
	v_add_f32_e32 v132, v133, v132
	v_add_f32_e32 v132, v146, v132
	v_mov_b32_e32 v133, v132
	s_nop 1
	v_permlane16_swap_b32 v132, v133
	s_waitcnt lgkmcnt(0)
	v_add_f32_e32 v132, v132, v133
	v_mov_b32_e32 v133, v132
	s_nop 1
	v_permlane32_swap_b32 v132, v133
	s_and_saveexec_b64 s[18:19], s[46:47]
	s_cbranch_execz .LBB0_289
	v_lshlrev_b64 v[128:129], 6, v[128:129]
	v_lshl_add_u64 v[128:129], s[28:29], 0, v[128:129]
	v_lshl_add_u64 v[128:129], s[60:61], 2, v[128:129]
	s_lshl_b32 s8, s78, 2
	v_lshl_add_u64 v[128:129], v[128:129], 0, s[8:9]
	s_waitcnt lgkmcnt(0)
	v_add_f32_e32 v132, v132, v133
	flat_store_dword v[128:129], v132
.LBB0_289:
	s_or_b64 exec, exec, s[18:19]
	v_add_u32_e32 v198, 128, v184
	v_ashrrev_i32_e32 v199, 31, v198
	v_lshlrev_b64 v[198:199], 10, v[198:199]
	v_lshl_add_u64 v[198:199], v[198:199], 0, v[182:183]
	v_lshl_add_u64 v[198:199], v[198:199], 2, s[16:17]
	global_load_dwordx4 v[96:99], v[198:199], off offset:528
	global_load_dwordx4 v[100:103], v[198:199], off offset:512
	v_add_u32_e32 v198, 144, v184
	v_ashrrev_i32_e32 v199, 31, v198
	v_lshlrev_b64 v[198:199], 10, v[198:199]
	v_lshl_add_u64 v[198:199], v[198:199], 0, v[182:183]
	v_lshl_add_u64 v[198:199], v[198:199], 2, s[16:17]
	global_load_dwordx4 v[104:107], v[198:199], off offset:16
	global_load_dwordx4 v[108:111], v[198:199], off
	global_load_dwordx4 v[214:217], v[198:199], off offset:528
	global_load_dwordx4 v[218:221], v[198:199], off offset:512
	v_add_u32_e32 v198, 160, v184
	v_ashrrev_i32_e32 v199, 31, v198
	v_lshlrev_b64 v[198:199], 10, v[198:199]
	v_lshl_add_u64 v[198:199], v[198:199], 0, v[182:183]
	v_lshl_add_u64 v[198:199], v[198:199], 2, s[16:17]
	global_load_dwordx4 v[224:227], v[198:199], off offset:16
	global_load_dwordx4 v[228:231], v[198:199], off
	v_or_b32_e32 v128, 32, v184
	v_ashrrev_i32_e32 v129, 31, v128
	s_waitcnt lgkmcnt(0)
	v_lshlrev_b64 v[132:133], 10, v[128:129]
	v_lshl_add_u64 v[140:141], v[132:133], 0, v[182:183]
	v_lshl_add_u64 v[142:143], v[140:141], 2, s[16:17]
	v_lshl_add_u64 v[140:141], v[140:141], 1, s[26:27]
	s_waitcnt vmcnt(17)
	v_pk_fma_f32 v[146:147], v[88:89], 0.5, v[232:233] op_sel_hi:[1,0,1]
	v_pk_fma_f32 v[138:139], v[94:95], 0.5, v[238:239] op_sel_hi:[1,0,1]
	v_pk_fma_f32 v[136:137], v[92:93], 0.5, v[236:237] op_sel_hi:[1,0,1]
	v_pk_fma_f32 v[144:145], v[90:91], 0.5, v[234:235] op_sel_hi:[1,0,1]
	v_cvt_pk_bf16_f32 v132, v136, v137
	v_cvt_pk_bf16_f32 v133, v138, v139
	v_cvt_pk_bf16_f32 v134, v146, v147
	s_nop 0
	v_cvt_pk_bf16_f32 v135, v144, v145
	global_store_dwordx4 v[140:141], v[132:135], off
	s_nop 1
	v_mul_f32_e32 v132, v137, v137
	v_mul_f32_e32 v133, v139, v139
	v_fmac_f32_e32 v132, v136, v136
	v_fmac_f32_e32 v133, v138, v138
	v_add_f32_e32 v132, v132, v133
	v_mul_f32_e32 v133, v147, v147
	v_fmac_f32_e32 v133, v146, v146
	v_add_f32_e32 v132, v133, v132
	v_mul_f32_e32 v133, v145, v145
	v_fmac_f32_e32 v133, v144, v144
	v_add_f32_e32 v146, v133, v132
	v_pk_fma_f32 v[144:145], v[80:81], 0.5, v[112:113] op_sel_hi:[1,0,1]
	v_pk_fma_f32 v[138:139], v[86:87], 0.5, v[118:119] op_sel_hi:[1,0,1]
	v_pk_fma_f32 v[136:137], v[84:85], 0.5, v[116:117] op_sel_hi:[1,0,1]
	v_pk_fma_f32 v[142:143], v[82:83], 0.5, v[114:115] op_sel_hi:[1,0,1]
	v_cvt_pk_bf16_f32 v132, v136, v137
	v_cvt_pk_bf16_f32 v133, v138, v139
	v_cvt_pk_bf16_f32 v134, v144, v145
	s_nop 0
	v_cvt_pk_bf16_f32 v135, v142, v143
	global_store_dwordx4 v[140:141], v[132:135], off offset:256
	s_nop 1
	v_mul_f32_e32 v132, v137, v137
	v_mul_f32_e32 v133, v139, v139
	v_fmac_f32_e32 v132, v136, v136
	v_fmac_f32_e32 v133, v138, v138
	v_add_f32_e32 v132, v132, v133
	v_mul_f32_e32 v133, v145, v145
	v_fmac_f32_e32 v133, v144, v144
	v_add_f32_e32 v132, v133, v132
	v_mul_f32_e32 v133, v143, v143
	v_fmac_f32_e32 v133, v142, v142
	v_add_f32_e32 v132, v133, v132
	v_add_f32_e32 v132, v146, v132
	v_mov_b32_e32 v133, v132
	s_nop 1
	v_permlane16_swap_b32 v132, v133
	s_waitcnt lgkmcnt(0)
	v_add_f32_e32 v132, v132, v133
	v_mov_b32_e32 v133, v132
	s_nop 1
	v_permlane32_swap_b32 v132, v133
	s_and_saveexec_b64 s[18:19], s[46:47]
	s_cbranch_execz .LBB0_291
	v_lshlrev_b64 v[128:129], 6, v[128:129]
	v_lshl_add_u64 v[128:129], s[28:29], 0, v[128:129]
	v_lshl_add_u64 v[128:129], s[60:61], 2, v[128:129]
	s_lshl_b32 s8, s78, 2
	v_lshl_add_u64 v[128:129], v[128:129], 0, s[8:9]
	s_waitcnt lgkmcnt(0)
	v_add_f32_e32 v132, v132, v133
	flat_store_dword v[128:129], v132
.LBB0_291:
	s_or_b64 exec, exec, s[18:19]
	v_add_u32_e32 v198, 160, v184
	v_ashrrev_i32_e32 v199, 31, v198
	v_lshlrev_b64 v[198:199], 10, v[198:199]
	v_lshl_add_u64 v[198:199], v[198:199], 0, v[182:183]
	v_lshl_add_u64 v[198:199], v[198:199], 2, s[16:17]
	global_load_dwordx4 v[80:83], v[198:199], off offset:528
	global_load_dwordx4 v[84:87], v[198:199], off offset:512
	v_add_u32_e32 v198, 176, v184
	v_ashrrev_i32_e32 v199, 31, v198
	v_lshlrev_b64 v[198:199], 10, v[198:199]
	v_lshl_add_u64 v[198:199], v[198:199], 0, v[182:183]
	v_lshl_add_u64 v[198:199], v[198:199], 2, s[16:17]
	global_load_dwordx4 v[88:91], v[198:199], off offset:16
	global_load_dwordx4 v[92:95], v[198:199], off
	global_load_dwordx4 v[232:235], v[198:199], off offset:528
	global_load_dwordx4 v[236:239], v[198:199], off offset:512
	v_or_b32_e32 v128, 48, v184
	v_ashrrev_i32_e32 v129, 31, v128
	s_waitcnt lgkmcnt(0)
	v_lshlrev_b64 v[132:133], 10, v[128:129]
	v_lshl_add_u64 v[140:141], v[132:133], 0, v[182:183]
	v_lshl_add_u64 v[142:143], v[140:141], 2, s[16:17]
	v_lshl_add_u64 v[140:141], v[140:141], 1, s[26:27]
	s_waitcnt vmcnt(22)
	v_pk_fma_f32 v[146:147], v[72:73], 0.5, v[120:121] op_sel_hi:[1,0,1]
	v_pk_fma_f32 v[138:139], v[78:79], 0.5, v[126:127] op_sel_hi:[1,0,1]
	v_pk_fma_f32 v[136:137], v[76:77], 0.5, v[124:125] op_sel_hi:[1,0,1]
	v_pk_fma_f32 v[144:145], v[74:75], 0.5, v[122:123] op_sel_hi:[1,0,1]
	v_cvt_pk_bf16_f32 v132, v136, v137
	v_cvt_pk_bf16_f32 v133, v138, v139
	v_cvt_pk_bf16_f32 v134, v146, v147
	s_nop 0
	v_cvt_pk_bf16_f32 v135, v144, v145
	global_store_dwordx4 v[140:141], v[132:135], off
	s_nop 1
	v_mul_f32_e32 v132, v137, v137
	v_mul_f32_e32 v133, v139, v139
	v_fmac_f32_e32 v132, v136, v136
	v_fmac_f32_e32 v133, v138, v138
	v_add_f32_e32 v132, v132, v133
	v_mul_f32_e32 v133, v147, v147
	v_fmac_f32_e32 v133, v146, v146
	v_add_f32_e32 v132, v133, v132
	v_mul_f32_e32 v133, v145, v145
	v_fmac_f32_e32 v133, v144, v144
	v_add_f32_e32 v146, v133, v132
	v_pk_fma_f32 v[144:145], v[64:65], 0.5, v[148:149] op_sel_hi:[1,0,1]
	v_pk_fma_f32 v[138:139], v[70:71], 0.5, v[188:189] op_sel_hi:[1,0,1]
	v_pk_fma_f32 v[136:137], v[68:69], 0.5, v[186:187] op_sel_hi:[1,0,1]
	v_pk_fma_f32 v[142:143], v[66:67], 0.5, v[150:151] op_sel_hi:[1,0,1]
	v_cvt_pk_bf16_f32 v132, v136, v137
	v_cvt_pk_bf16_f32 v133, v138, v139
	v_cvt_pk_bf16_f32 v134, v144, v145
	s_nop 0
	v_cvt_pk_bf16_f32 v135, v142, v143
	global_store_dwordx4 v[140:141], v[132:135], off offset:256
	s_nop 1
	v_mul_f32_e32 v132, v137, v137
	v_mul_f32_e32 v133, v139, v139
	v_fmac_f32_e32 v132, v136, v136
	v_fmac_f32_e32 v133, v138, v138
	v_add_f32_e32 v132, v132, v133
	v_mul_f32_e32 v133, v145, v145
	v_fmac_f32_e32 v133, v144, v144
	v_add_f32_e32 v132, v133, v132
	v_mul_f32_e32 v133, v143, v143
	v_fmac_f32_e32 v133, v142, v142
	v_add_f32_e32 v132, v133, v132
	v_add_f32_e32 v132, v146, v132
	v_mov_b32_e32 v133, v132
	s_nop 1
	v_permlane16_swap_b32 v132, v133
	s_waitcnt lgkmcnt(0)
	v_add_f32_e32 v132, v132, v133
	v_mov_b32_e32 v133, v132
	s_nop 1
	v_permlane32_swap_b32 v132, v133
	s_and_saveexec_b64 s[18:19], s[46:47]
	s_cbranch_execz .LBB0_293
	v_lshlrev_b64 v[128:129], 6, v[128:129]
	v_lshl_add_u64 v[128:129], s[28:29], 0, v[128:129]
	v_lshl_add_u64 v[128:129], s[60:61], 2, v[128:129]
	s_lshl_b32 s8, s78, 2
	v_lshl_add_u64 v[128:129], v[128:129], 0, s[8:9]
	s_waitcnt lgkmcnt(0)
	v_add_f32_e32 v132, v132, v133
	flat_store_dword v[128:129], v132
.LBB0_293:
	s_or_b64 exec, exec, s[18:19]
	v_add_u32_e32 v128, 0x80, v184
	v_ashrrev_i32_e32 v129, 31, v128
	s_waitcnt lgkmcnt(0)
	v_lshlrev_b64 v[132:133], 10, v[128:129]
	v_lshl_add_u64 v[140:141], v[132:133], 0, v[182:183]
	v_lshl_add_u64 v[142:143], v[140:141], 2, s[16:17]
	v_lshl_add_u64 v[140:141], v[140:141], 1, s[26:27]
	s_waitcnt vmcnt(18)
	v_pk_fma_f32 v[146:147], v[56:57], 0.5, v[190:191] op_sel_hi:[1,0,1]
	v_pk_fma_f32 v[138:139], v[62:63], 0.5, v[196:197] op_sel_hi:[1,0,1]
	v_pk_fma_f32 v[136:137], v[60:61], 0.5, v[194:195] op_sel_hi:[1,0,1]
	v_pk_fma_f32 v[144:145], v[58:59], 0.5, v[192:193] op_sel_hi:[1,0,1]
	v_cvt_pk_bf16_f32 v132, v136, v137
	v_cvt_pk_bf16_f32 v133, v138, v139
	v_cvt_pk_bf16_f32 v134, v146, v147
	s_nop 0
	v_cvt_pk_bf16_f32 v135, v144, v145
	global_store_dwordx4 v[140:141], v[132:135], off
	s_nop 1
	v_mul_f32_e32 v132, v137, v137
	v_mul_f32_e32 v133, v139, v139
	v_fmac_f32_e32 v132, v136, v136
	v_fmac_f32_e32 v133, v138, v138
	v_add_f32_e32 v132, v132, v133
	v_mul_f32_e32 v133, v147, v147
	v_fmac_f32_e32 v133, v146, v146
	v_add_f32_e32 v132, v133, v132
	v_mul_f32_e32 v133, v145, v145
	v_fmac_f32_e32 v133, v144, v144
	v_add_f32_e32 v146, v133, v132
	v_pk_fma_f32 v[144:145], v[48:49], 0.5, v[96:97] op_sel_hi:[1,0,1]
	v_pk_fma_f32 v[138:139], v[54:55], 0.5, v[102:103] op_sel_hi:[1,0,1]
	v_pk_fma_f32 v[136:137], v[52:53], 0.5, v[100:101] op_sel_hi:[1,0,1]
	v_pk_fma_f32 v[142:143], v[50:51], 0.5, v[98:99] op_sel_hi:[1,0,1]
	v_cvt_pk_bf16_f32 v132, v136, v137
	v_cvt_pk_bf16_f32 v133, v138, v139
	v_cvt_pk_bf16_f32 v134, v144, v145
	s_nop 0
	v_cvt_pk_bf16_f32 v135, v142, v143
	global_store_dwordx4 v[140:141], v[132:135], off offset:256
	s_nop 1
	v_mul_f32_e32 v132, v137, v137
	v_mul_f32_e32 v133, v139, v139
	v_fmac_f32_e32 v132, v136, v136
	v_fmac_f32_e32 v133, v138, v138
	v_add_f32_e32 v132, v132, v133
	v_mul_f32_e32 v133, v145, v145
	v_fmac_f32_e32 v133, v144, v144
	v_add_f32_e32 v132, v133, v132
	v_mul_f32_e32 v133, v143, v143
	v_fmac_f32_e32 v133, v142, v142
	v_add_f32_e32 v132, v133, v132
	v_add_f32_e32 v132, v146, v132
	v_mov_b32_e32 v133, v132
	s_nop 1
	v_permlane16_swap_b32 v132, v133
	s_waitcnt lgkmcnt(0)
	v_add_f32_e32 v132, v132, v133
	v_mov_b32_e32 v133, v132
	s_nop 1
	v_permlane32_swap_b32 v132, v133
	s_and_saveexec_b64 s[18:19], s[46:47]
	s_cbranch_execz .LBB0_295
	v_lshlrev_b64 v[128:129], 6, v[128:129]
	v_lshl_add_u64 v[128:129], s[28:29], 0, v[128:129]
	v_lshl_add_u64 v[128:129], s[60:61], 2, v[128:129]
	s_lshl_b32 s8, s78, 2
	v_lshl_add_u64 v[128:129], v[128:129], 0, s[8:9]
	s_waitcnt lgkmcnt(0)
	v_add_f32_e32 v132, v132, v133
	flat_store_dword v[128:129], v132
.LBB0_295:
	s_or_b64 exec, exec, s[18:19]
	v_add_u32_e32 v128, 0x90, v184
	v_ashrrev_i32_e32 v129, 31, v128
	s_waitcnt lgkmcnt(0)
	v_lshlrev_b64 v[132:133], 10, v[128:129]
	v_lshl_add_u64 v[140:141], v[132:133], 0, v[182:183]
	v_lshl_add_u64 v[142:143], v[140:141], 2, s[16:17]
	v_lshl_add_u64 v[140:141], v[140:141], 1, s[26:27]
	s_waitcnt vmcnt(17)
	v_pk_fma_f32 v[146:147], v[40:41], 0.5, v[104:105] op_sel_hi:[1,0,1]
	v_pk_fma_f32 v[138:139], v[46:47], 0.5, v[110:111] op_sel_hi:[1,0,1]
	v_pk_fma_f32 v[136:137], v[44:45], 0.5, v[108:109] op_sel_hi:[1,0,1]
	v_pk_fma_f32 v[144:145], v[42:43], 0.5, v[106:107] op_sel_hi:[1,0,1]
	v_cvt_pk_bf16_f32 v132, v136, v137
	v_cvt_pk_bf16_f32 v133, v138, v139
	v_cvt_pk_bf16_f32 v134, v146, v147
	s_nop 0
	v_cvt_pk_bf16_f32 v135, v144, v145
	global_store_dwordx4 v[140:141], v[132:135], off
	s_nop 1
	v_mul_f32_e32 v132, v137, v137
	v_mul_f32_e32 v133, v139, v139
	v_fmac_f32_e32 v132, v136, v136
	v_fmac_f32_e32 v133, v138, v138
	v_add_f32_e32 v132, v132, v133
	v_mul_f32_e32 v133, v147, v147
	v_fmac_f32_e32 v133, v146, v146
	v_add_f32_e32 v132, v133, v132
	v_mul_f32_e32 v133, v145, v145
	v_fmac_f32_e32 v133, v144, v144
	v_add_f32_e32 v146, v133, v132
	v_pk_fma_f32 v[144:145], v[32:33], 0.5, v[214:215] op_sel_hi:[1,0,1]
	v_pk_fma_f32 v[138:139], v[38:39], 0.5, v[220:221] op_sel_hi:[1,0,1]
	v_pk_fma_f32 v[136:137], v[36:37], 0.5, v[218:219] op_sel_hi:[1,0,1]
	v_pk_fma_f32 v[142:143], v[34:35], 0.5, v[216:217] op_sel_hi:[1,0,1]
	v_cvt_pk_bf16_f32 v132, v136, v137
	v_cvt_pk_bf16_f32 v133, v138, v139
	v_cvt_pk_bf16_f32 v134, v144, v145
	s_nop 0
	v_cvt_pk_bf16_f32 v135, v142, v143
	global_store_dwordx4 v[140:141], v[132:135], off offset:256
	s_nop 1
	v_mul_f32_e32 v132, v137, v137
	v_mul_f32_e32 v133, v139, v139
	v_fmac_f32_e32 v132, v136, v136
	v_fmac_f32_e32 v133, v138, v138
	v_add_f32_e32 v132, v132, v133
	v_mul_f32_e32 v133, v145, v145
	v_fmac_f32_e32 v133, v144, v144
	v_add_f32_e32 v132, v133, v132
	v_mul_f32_e32 v133, v143, v143
	v_fmac_f32_e32 v133, v142, v142
	v_add_f32_e32 v132, v133, v132
	v_add_f32_e32 v132, v146, v132
	v_mov_b32_e32 v133, v132
	s_nop 1
	v_permlane16_swap_b32 v132, v133
	s_waitcnt lgkmcnt(0)
	v_add_f32_e32 v132, v132, v133
	v_mov_b32_e32 v133, v132
	s_nop 1
	v_permlane32_swap_b32 v132, v133
	s_and_saveexec_b64 s[18:19], s[46:47]
	s_cbranch_execz .LBB0_297
	v_lshlrev_b64 v[128:129], 6, v[128:129]
	v_lshl_add_u64 v[128:129], s[28:29], 0, v[128:129]
	v_lshl_add_u64 v[128:129], s[60:61], 2, v[128:129]
	s_lshl_b32 s8, s78, 2
	v_lshl_add_u64 v[128:129], v[128:129], 0, s[8:9]
	s_waitcnt lgkmcnt(0)
	v_add_f32_e32 v132, v132, v133
	flat_store_dword v[128:129], v132
.LBB0_297:
	s_or_b64 exec, exec, s[18:19]
	v_add_u32_e32 v128, 0xa0, v184
	v_ashrrev_i32_e32 v129, 31, v128
	s_waitcnt lgkmcnt(0)
	v_lshlrev_b64 v[132:133], 10, v[128:129]
	v_lshl_add_u64 v[140:141], v[132:133], 0, v[182:183]
	v_lshl_add_u64 v[142:143], v[140:141], 2, s[16:17]
	v_lshl_add_u64 v[140:141], v[140:141], 1, s[26:27]
	s_waitcnt vmcnt(13)
	v_pk_fma_f32 v[146:147], v[24:25], 0.5, v[224:225] op_sel_hi:[1,0,1]
	v_pk_fma_f32 v[138:139], v[30:31], 0.5, v[230:231] op_sel_hi:[1,0,1]
	v_pk_fma_f32 v[136:137], v[28:29], 0.5, v[228:229] op_sel_hi:[1,0,1]
	v_pk_fma_f32 v[144:145], v[26:27], 0.5, v[226:227] op_sel_hi:[1,0,1]
	v_cvt_pk_bf16_f32 v132, v136, v137
	v_cvt_pk_bf16_f32 v133, v138, v139
	v_cvt_pk_bf16_f32 v134, v146, v147
	s_nop 0
	v_cvt_pk_bf16_f32 v135, v144, v145
	global_store_dwordx4 v[140:141], v[132:135], off
	s_nop 1
	v_mul_f32_e32 v132, v137, v137
	v_mul_f32_e32 v133, v139, v139
	v_fmac_f32_e32 v132, v136, v136
	v_fmac_f32_e32 v133, v138, v138
	v_add_f32_e32 v132, v132, v133
	v_mul_f32_e32 v133, v147, v147
	v_fmac_f32_e32 v133, v146, v146
	v_add_f32_e32 v132, v133, v132
	v_mul_f32_e32 v133, v145, v145
	v_fmac_f32_e32 v133, v144, v144
	v_add_f32_e32 v146, v133, v132
	v_pk_fma_f32 v[144:145], v[16:17], 0.5, v[80:81] op_sel_hi:[1,0,1]
	v_pk_fma_f32 v[138:139], v[22:23], 0.5, v[86:87] op_sel_hi:[1,0,1]
	v_pk_fma_f32 v[136:137], v[20:21], 0.5, v[84:85] op_sel_hi:[1,0,1]
	v_pk_fma_f32 v[142:143], v[18:19], 0.5, v[82:83] op_sel_hi:[1,0,1]
	v_cvt_pk_bf16_f32 v132, v136, v137
	v_cvt_pk_bf16_f32 v133, v138, v139
	v_cvt_pk_bf16_f32 v134, v144, v145
	s_nop 0
	v_cvt_pk_bf16_f32 v135, v142, v143
	global_store_dwordx4 v[140:141], v[132:135], off offset:256
	s_nop 1
	v_mul_f32_e32 v132, v137, v137
	v_mul_f32_e32 v133, v139, v139
	v_fmac_f32_e32 v132, v136, v136
	v_fmac_f32_e32 v133, v138, v138
	v_add_f32_e32 v132, v132, v133
	v_mul_f32_e32 v133, v145, v145
	v_fmac_f32_e32 v133, v144, v144
	v_add_f32_e32 v132, v133, v132
	v_mul_f32_e32 v133, v143, v143
	v_fmac_f32_e32 v133, v142, v142
	v_add_f32_e32 v132, v133, v132
	v_add_f32_e32 v132, v146, v132
	v_mov_b32_e32 v133, v132
	s_nop 1
	v_permlane16_swap_b32 v132, v133
	s_waitcnt lgkmcnt(0)
	v_add_f32_e32 v132, v132, v133
	v_mov_b32_e32 v133, v132
	s_nop 1
	v_permlane32_swap_b32 v132, v133
	s_and_saveexec_b64 s[18:19], s[46:47]
	s_cbranch_execz .LBB0_299
	v_lshlrev_b64 v[128:129], 6, v[128:129]
	v_lshl_add_u64 v[128:129], s[28:29], 0, v[128:129]
	v_lshl_add_u64 v[128:129], s[60:61], 2, v[128:129]
	s_lshl_b32 s8, s78, 2
	v_lshl_add_u64 v[128:129], v[128:129], 0, s[8:9]
	s_waitcnt lgkmcnt(0)
	v_add_f32_e32 v132, v132, v133
	flat_store_dword v[128:129], v132
.LBB0_299:
	s_or_b64 exec, exec, s[18:19]
	v_add_u32_e32 v128, 0xb0, v184
	v_ashrrev_i32_e32 v129, 31, v128
	s_waitcnt lgkmcnt(0)
	v_lshlrev_b64 v[132:133], 10, v[128:129]
	v_lshl_add_u64 v[140:141], v[132:133], 0, v[182:183]
	v_lshl_add_u64 v[142:143], v[140:141], 2, s[16:17]
	v_lshl_add_u64 v[140:141], v[140:141], 1, s[26:27]
	s_waitcnt vmcnt(12)
	v_pk_fma_f32 v[146:147], v[8:9], 0.5, v[88:89] op_sel_hi:[1,0,1]
	v_pk_fma_f32 v[138:139], v[14:15], 0.5, v[94:95] op_sel_hi:[1,0,1]
	v_pk_fma_f32 v[136:137], v[12:13], 0.5, v[92:93] op_sel_hi:[1,0,1]
	v_pk_fma_f32 v[144:145], v[10:11], 0.5, v[90:91] op_sel_hi:[1,0,1]
	v_cvt_pk_bf16_f32 v132, v136, v137
	v_cvt_pk_bf16_f32 v133, v138, v139
	v_cvt_pk_bf16_f32 v134, v146, v147
	s_nop 0
	v_cvt_pk_bf16_f32 v135, v144, v145
	global_store_dwordx4 v[140:141], v[132:135], off
	s_nop 1
	v_mul_f32_e32 v132, v137, v137
	v_mul_f32_e32 v133, v139, v139
	v_fmac_f32_e32 v132, v136, v136
	v_fmac_f32_e32 v133, v138, v138
	v_add_f32_e32 v132, v132, v133
	v_mul_f32_e32 v133, v147, v147
	v_fmac_f32_e32 v133, v146, v146
	v_add_f32_e32 v132, v133, v132
	v_mul_f32_e32 v133, v145, v145
	v_fmac_f32_e32 v133, v144, v144
	v_add_f32_e32 v146, v133, v132
	v_pk_fma_f32 v[144:145], v[0:1], 0.5, v[232:233] op_sel_hi:[1,0,1]
	v_pk_fma_f32 v[138:139], v[6:7], 0.5, v[238:239] op_sel_hi:[1,0,1]
	v_pk_fma_f32 v[136:137], v[4:5], 0.5, v[236:237] op_sel_hi:[1,0,1]
	v_pk_fma_f32 v[142:143], v[2:3], 0.5, v[234:235] op_sel_hi:[1,0,1]
	v_cvt_pk_bf16_f32 v132, v136, v137
	v_cvt_pk_bf16_f32 v133, v138, v139
	v_cvt_pk_bf16_f32 v134, v144, v145
	s_nop 0
	v_cvt_pk_bf16_f32 v135, v142, v143
	global_store_dwordx4 v[140:141], v[132:135], off offset:256
	s_nop 1
	v_mul_f32_e32 v132, v137, v137
	v_mul_f32_e32 v133, v139, v139
	v_fmac_f32_e32 v132, v136, v136
	v_fmac_f32_e32 v133, v138, v138
	v_add_f32_e32 v132, v132, v133
	v_mul_f32_e32 v133, v145, v145
	v_fmac_f32_e32 v133, v144, v144
	v_add_f32_e32 v132, v133, v132
	v_mul_f32_e32 v133, v143, v143
	v_fmac_f32_e32 v133, v142, v142
	v_add_f32_e32 v132, v133, v132
	v_add_f32_e32 v132, v146, v132
	v_mov_b32_e32 v130, v132
	s_nop 1
	v_permlane16_swap_b32 v132, v130
	s_waitcnt lgkmcnt(0)
	v_add_f32_e32 v130, v132, v130
	v_mov_b32_e32 v131, v130
	s_nop 1
	v_permlane32_swap_b32 v130, v131
	s_and_saveexec_b64 s[18:19], s[46:47]
	s_cbranch_execz .LBB0_301
	v_lshlrev_b64 v[128:129], 6, v[128:129]
	v_lshl_add_u64 v[128:129], s[28:29], 0, v[128:129]
	v_lshl_add_u64 v[128:129], s[60:61], 2, v[128:129]
	s_lshl_b32 s8, s78, 2
	v_lshl_add_u64 v[128:129], v[128:129], 0, s[8:9]
	s_waitcnt lgkmcnt(0)
	v_add_f32_e32 v130, v130, v131
	flat_store_dword v[128:129], v130

.LBB0_303:
	s_cbranch_execz .LBB0_302
	v_lshlrev_b64 v[186:187], 1, v[182:183]
	v_lshl_add_u64 v[128:129], s[26:27], 0, v[186:187]
	v_lshlrev_b64 v[224:225], 11, v[184:185]
	s_waitcnt lgkmcnt(0)
	v_lshl_add_u64 v[130:131], v[128:129], 0, v[224:225]
	global_load_dwordx4 v[214:217], v[130:131], off
	global_load_dwordx4 v[218:221], v[130:131], off offset:256
	v_or_b32_e32 v196, 16, v184
	v_ashrrev_i32_e32 v197, 31, v196
	v_or_b32_e32 v192, 32, v184
	v_or_b32_e32 v188, 48, v184
	v_lshlrev_b64 v[198:199], 11, v[196:197]
	v_ashrrev_i32_e32 v193, 31, v192
	v_ashrrev_i32_e32 v189, 31, v188
	v_lshl_add_u64 v[130:131], v[128:129], 0, v[198:199]
	v_lshlrev_b64 v[194:195], 11, v[192:193]
	v_lshlrev_b64 v[190:191], 11, v[188:189]
	global_load_dwordx4 v[148:151], v[130:131], off
	global_load_dwordx4 v[144:147], v[130:131], off offset:256
	v_lshl_add_u64 v[130:131], v[128:129], 0, v[194:195]
	v_lshl_add_u64 v[128:129], v[128:129], 0, v[190:191]
	global_load_dwordx4 v[140:143], v[130:131], off
	global_load_dwordx4 v[136:139], v[130:131], off offset:256
	global_load_dwordx4 v[132:135], v[128:129], off
	s_nop 0
	global_load_dwordx4 v[128:131], v[128:129], off offset:256
	s_lshl_b32 s60, s83, 2
	s_ashr_i32 s61, s60, 31
	s_waitcnt vmcnt(0)
	v_lshlrev_b32_e32 v226, 16, v215
	v_lshlrev_b32_e32 v213, 16, v214
	v_and_b32_e32 v214, 0xffff0000, v214
	v_fmac_f32_e32 v226, 0.5, v126
	v_and_b32_e32 v126, 0xffff0000, v215
	v_fmac_f32_e32 v213, 0.5, v124
	v_fmac_f32_e32 v214, 0.5, v125
	v_fmac_f32_e32 v126, 0.5, v127
	v_lshlrev_b32_e32 v127, 16, v216
	v_and_b32_e32 v215, 0xffff0000, v216
	v_lshl_add_u64 v[124:125], s[26:27], 0, v[224:225]
	v_fmac_f32_e32 v127, 0.5, v120
	v_fmac_f32_e32 v215, 0.5, v121
	v_lshlrev_b32_e32 v216, 16, v217
	v_and_b32_e32 v217, 0xffff0000, v217
	v_cvt_pk_bf16_f32 v120, v213, v214
	v_cvt_pk_bf16_f32 v121, v226, v126
	v_lshl_add_u64 v[124:125], v[124:125], 0, v[186:187]
	v_fmac_f32_e32 v216, 0.5, v122
	v_fmac_f32_e32 v217, 0.5, v123
	v_cvt_pk_bf16_f32 v122, v127, v215
	v_cvt_pk_bf16_f32 v123, v216, v217
	global_store_dwordx4 v[124:125], v[120:123], off
	s_nop 1
	v_mul_f32_e32 v120, v214, v214
	v_mul_f32_e32 v121, v126, v126
	v_fmac_f32_e32 v120, v213, v213
	v_fmac_f32_e32 v121, v226, v226
	v_add_f32_e32 v120, v120, v121
	v_mul_f32_e32 v121, v215, v215
	v_fmac_f32_e32 v121, v127, v127
	v_add_f32_e32 v120, v121, v120
	v_mul_f32_e32 v121, v217, v217
	v_fmac_f32_e32 v121, v216, v216
	v_add_f32_e32 v120, v121, v120
	v_lshlrev_b32_e32 v121, 16, v218
	v_fmac_f32_e32 v121, 0.5, v116
	v_and_b32_e32 v116, 0xffff0000, v218
	v_fmac_f32_e32 v116, 0.5, v117
	v_lshlrev_b32_e32 v117, 16, v219
	v_fmac_f32_e32 v117, 0.5, v118
	v_and_b32_e32 v118, 0xffff0000, v219
	v_fmac_f32_e32 v118, 0.5, v119
	v_lshlrev_b32_e32 v119, 16, v220
	v_and_b32_e32 v122, 0xffff0000, v220
	v_fmac_f32_e32 v119, 0.5, v112
	v_fmac_f32_e32 v122, 0.5, v113
	v_lshlrev_b32_e32 v123, 16, v221
	v_and_b32_e32 v126, 0xffff0000, v221
	v_cvt_pk_bf16_f32 v112, v121, v116
	v_cvt_pk_bf16_f32 v113, v117, v118
	v_fmac_f32_e32 v123, 0.5, v114
	v_fmac_f32_e32 v126, 0.5, v115
	v_cvt_pk_bf16_f32 v114, v119, v122
	v_cvt_pk_bf16_f32 v115, v123, v126
	global_store_dwordx4 v[124:125], v[112:115], off offset:256
	s_nop 1
	v_mul_f32_e32 v112, v116, v116
	v_mul_f32_e32 v113, v118, v118
	v_fmac_f32_e32 v112, v121, v121
	v_fmac_f32_e32 v113, v117, v117
	v_add_f32_e32 v112, v112, v113
	v_mul_f32_e32 v113, v122, v122
	v_fmac_f32_e32 v113, v119, v119
	v_add_f32_e32 v112, v113, v112
	v_mul_f32_e32 v113, v126, v126
	v_fmac_f32_e32 v113, v123, v123
	v_add_f32_e32 v112, v113, v112
	v_xor_b32_e32 v113, 16, v204
	v_cmp_lt_i32_e32 vcc, v113, v205
	v_add_f32_e32 v112, v120, v112
	s_nop 0
	v_cndmask_b32_e32 v113, v204, v113, vcc
	v_lshlrev_b32_e32 v124, 2, v113
	v_mov_b32_e32 v113, v112
	s_nop 1
	v_permlane16_swap_b32 v112, v113
	s_waitcnt lgkmcnt(0)
	v_add_f32_e32 v112, v112, v113
	v_xor_b32_e32 v113, 32, v204
	v_cmp_lt_i32_e32 vcc, v113, v205
	s_nop 1
	v_cndmask_b32_e32 v113, v204, v113, vcc
	v_lshlrev_b32_e32 v125, 2, v113
	v_mov_b32_e32 v113, v112
	s_nop 1
	v_permlane32_swap_b32 v112, v113
	s_and_saveexec_b64 s[18:19], s[46:47]
	s_cbranch_execz .LBB0_306
	v_lshlrev_b64 v[114:115], 6, v[184:185]
	v_lshl_add_u64 v[114:115], s[28:29], 0, v[114:115]
	v_lshl_add_u64 v[114:115], s[60:61], 2, v[114:115]
	s_lshl_b32 s8, s78, 2
	v_lshl_add_u64 v[114:115], v[114:115], 0, s[8:9]
	s_waitcnt lgkmcnt(0)
	v_add_f32_e32 v112, v112, v113
	flat_store_dword v[114:115], v112
.LBB0_306:
	s_or_b64 exec, exec, s[18:19]
	v_add_u32_e32 v120, 0x80, v184
	v_ashrrev_i32_e32 v121, 31, v120
	s_waitcnt lgkmcnt(0)
	v_lshlrev_b64 v[112:113], 11, v[120:121]
	v_lshl_add_u64 v[112:113], s[26:27], 0, v[112:113]
	v_lshl_add_u64 v[122:123], v[112:113], 0, v[186:187]
	global_load_dwordx4 v[116:119], v[122:123], off
	global_load_dwordx4 v[112:115], v[122:123], off offset:256
	v_lshlrev_b32_e32 v126, 16, v148
	v_fmac_f32_e32 v126, 0.5, v108
	v_and_b32_e32 v108, 0xffff0000, v148
	v_fmac_f32_e32 v108, 0.5, v109
	v_lshlrev_b32_e32 v109, 16, v149
	v_fmac_f32_e32 v109, 0.5, v110
	v_and_b32_e32 v110, 0xffff0000, v149
	v_fmac_f32_e32 v110, 0.5, v111
	v_lshlrev_b32_e32 v111, 16, v150
	v_and_b32_e32 v127, 0xffff0000, v150
	v_fmac_f32_e32 v111, 0.5, v104
	v_fmac_f32_e32 v127, 0.5, v105
	v_cvt_pk_bf16_f32 v104, v126, v108
	v_cvt_pk_bf16_f32 v105, v109, v110
	v_mul_f32_e32 v108, v108, v108
	v_mul_f32_e32 v110, v110, v110
	v_and_b32_e32 v149, 0xffff0000, v151
	v_fmac_f32_e32 v108, v126, v126
	v_fmac_f32_e32 v110, v109, v109
	v_mul_f32_e32 v109, v127, v127
	v_lshlrev_b32_e32 v148, 16, v151
	v_fmac_f32_e32 v149, 0.5, v107
	v_add_f32_e32 v108, v108, v110
	v_fmac_f32_e32 v109, v111, v111
	v_fmac_f32_e32 v148, 0.5, v106
	v_add_f32_e32 v108, v109, v108
	v_mul_f32_e32 v109, v149, v149
	v_fmac_f32_e32 v109, v148, v148
	v_add_f32_e32 v108, v109, v108
	v_lshlrev_b32_e32 v109, 16, v144
	v_fmac_f32_e32 v109, 0.5, v100
	v_and_b32_e32 v100, 0xffff0000, v144
	v_and_b32_e32 v110, 0xffff0000, v145
	v_cvt_pk_bf16_f32 v106, v111, v127
	v_fmac_f32_e32 v100, 0.5, v101
	v_lshlrev_b32_e32 v101, 16, v145
	v_fmac_f32_e32 v110, 0.5, v103
	v_lshlrev_b32_e32 v111, 16, v146
	v_and_b32_e32 v126, 0xffff0000, v146
	v_fmac_f32_e32 v101, 0.5, v102
	v_fmac_f32_e32 v111, 0.5, v96
	v_fmac_f32_e32 v126, 0.5, v97
	v_mul_f32_e32 v96, v100, v100
	v_mul_f32_e32 v97, v110, v110
	v_fmac_f32_e32 v96, v109, v109
	v_fmac_f32_e32 v97, v101, v101
	v_and_b32_e32 v144, 0xffff0000, v147
	v_add_f32_e32 v96, v96, v97
	v_mul_f32_e32 v97, v126, v126
	v_lshlrev_b32_e32 v127, 16, v147
	v_fmac_f32_e32 v144, 0.5, v99
	v_fmac_f32_e32 v97, v111, v111
	v_fmac_f32_e32 v127, 0.5, v98
	v_add_f32_e32 v96, v97, v96
	v_mul_f32_e32 v97, v144, v144
	v_fmac_f32_e32 v97, v127, v127
	v_add_f32_e32 v96, v97, v96
	v_add_f32_e32 v99, v108, v96
	v_mov_b32_e32 v108, v99
	s_nop 1
	v_permlane16_swap_b32 v99, v108
	v_lshl_add_u64 v[96:97], s[26:27], 0, v[198:199]
	v_lshl_add_u64 v[102:103], v[96:97], 0, v[186:187]
	v_cvt_pk_bf16_f32 v107, v148, v149
	global_store_dwordx4 v[102:103], v[104:107], off
	s_waitcnt lgkmcnt(0)
	v_add_f32_e32 v96, v99, v108
	v_mov_b32_e32 v97, v96
	s_nop 1
	v_permlane32_swap_b32 v96, v97
	v_cvt_pk_bf16_f32 v98, v109, v100
	v_cvt_pk_bf16_f32 v99, v101, v110
	v_cvt_pk_bf16_f32 v100, v111, v126
	v_cvt_pk_bf16_f32 v101, v127, v144
	global_store_dwordx4 v[102:103], v[98:101], off offset:256
	s_and_saveexec_b64 s[18:19], s[46:47]
	s_cbranch_execz .LBB0_308
	v_lshlrev_b64 v[98:99], 6, v[196:197]
	v_lshl_add_u64 v[98:99], s[28:29], 0, v[98:99]
	v_lshl_add_u64 v[98:99], s[60:61], 2, v[98:99]
	s_lshl_b32 s8, s78, 2
	v_lshl_add_u64 v[98:99], v[98:99], 0, s[8:9]
	s_waitcnt lgkmcnt(0)
	v_add_f32_e32 v96, v96, v97
	flat_store_dword v[98:99], v96
.LBB0_308:
	s_or_b64 exec, exec, s[18:19]
	v_or_b32_e32 v104, 16, v120
	v_ashrrev_i32_e32 v105, 31, v104
	s_waitcnt lgkmcnt(0)
	v_lshlrev_b64 v[96:97], 11, v[104:105]
	v_lshl_add_u64 v[96:97], s[26:27], 0, v[96:97]
	v_lshl_add_u64 v[106:107], v[96:97], 0, v[186:187]
	global_load_dwordx4 v[100:103], v[106:107], off
	global_load_dwordx4 v[96:99], v[106:107], off offset:256
	v_lshlrev_b32_e32 v108, 16, v140
	v_fmac_f32_e32 v108, 0.5, v92
	v_and_b32_e32 v92, 0xffff0000, v140
	v_fmac_f32_e32 v92, 0.5, v93
	v_lshlrev_b32_e32 v93, 16, v141
	v_fmac_f32_e32 v93, 0.5, v94
	v_and_b32_e32 v94, 0xffff0000, v141
	v_fmac_f32_e32 v94, 0.5, v95
	v_lshlrev_b32_e32 v95, 16, v142
	v_and_b32_e32 v109, 0xffff0000, v142
	v_fmac_f32_e32 v95, 0.5, v88
	v_fmac_f32_e32 v109, 0.5, v89
	v_cvt_pk_bf16_f32 v88, v108, v92
	v_cvt_pk_bf16_f32 v89, v93, v94
	v_mul_f32_e32 v92, v92, v92
	v_mul_f32_e32 v94, v94, v94
	v_and_b32_e32 v111, 0xffff0000, v143
	v_fmac_f32_e32 v92, v108, v108
	v_fmac_f32_e32 v94, v93, v93
	v_mul_f32_e32 v93, v109, v109
	v_lshlrev_b32_e32 v110, 16, v143
	v_fmac_f32_e32 v111, 0.5, v91
	v_add_f32_e32 v92, v92, v94
	v_fmac_f32_e32 v93, v95, v95
	v_fmac_f32_e32 v110, 0.5, v90
	v_add_f32_e32 v92, v93, v92
	v_mul_f32_e32 v93, v111, v111
	v_fmac_f32_e32 v93, v110, v110
	v_add_f32_e32 v92, v93, v92
	v_lshlrev_b32_e32 v93, 16, v136
	v_fmac_f32_e32 v93, 0.5, v84
	v_and_b32_e32 v84, 0xffff0000, v136
	v_and_b32_e32 v94, 0xffff0000, v137
	v_cvt_pk_bf16_f32 v90, v95, v109
	v_fmac_f32_e32 v84, 0.5, v85
	v_lshlrev_b32_e32 v85, 16, v137
	v_fmac_f32_e32 v94, 0.5, v87
	v_lshlrev_b32_e32 v95, 16, v138
	v_and_b32_e32 v108, 0xffff0000, v138
	v_fmac_f32_e32 v85, 0.5, v86
	v_fmac_f32_e32 v95, 0.5, v80
	v_fmac_f32_e32 v108, 0.5, v81
	v_mul_f32_e32 v80, v84, v84
	v_mul_f32_e32 v81, v94, v94
	v_fmac_f32_e32 v80, v93, v93
	v_fmac_f32_e32 v81, v85, v85
	v_cvt_pk_bf16_f32 v91, v110, v111
	v_and_b32_e32 v110, 0xffff0000, v139
	v_add_f32_e32 v80, v80, v81
	v_mul_f32_e32 v81, v108, v108
	v_lshlrev_b32_e32 v109, 16, v139
	v_fmac_f32_e32 v110, 0.5, v83
	v_fmac_f32_e32 v81, v95, v95
	v_fmac_f32_e32 v109, 0.5, v82
	v_add_f32_e32 v80, v81, v80
	v_mul_f32_e32 v81, v110, v110
	v_fmac_f32_e32 v81, v109, v109
	v_add_f32_e32 v80, v81, v80
	v_add_f32_e32 v83, v92, v80
	v_mov_b32_e32 v92, v83
	s_nop 1
	v_permlane16_swap_b32 v83, v92
	v_lshl_add_u64 v[80:81], s[26:27], 0, v[194:195]
	v_lshl_add_u64 v[86:87], v[80:81], 0, v[186:187]
	global_store_dwordx4 v[86:87], v[88:91], off
	v_cvt_pk_bf16_f32 v82, v93, v84
	s_waitcnt lgkmcnt(0)
	v_add_f32_e32 v80, v83, v92
	v_mov_b32_e32 v81, v80
	s_nop 1
	v_permlane32_swap_b32 v80, v81
	v_cvt_pk_bf16_f32 v83, v85, v94
	v_cvt_pk_bf16_f32 v84, v95, v108
	v_cvt_pk_bf16_f32 v85, v109, v110
	global_store_dwordx4 v[86:87], v[82:85], off offset:256
	s_and_saveexec_b64 s[18:19], s[46:47]
	s_cbranch_execz .LBB0_310
	v_lshlrev_b64 v[82:83], 6, v[192:193]
	v_lshl_add_u64 v[82:83], s[28:29], 0, v[82:83]
	v_lshl_add_u64 v[82:83], s[60:61], 2, v[82:83]
	s_lshl_b32 s8, s78, 2
	v_lshl_add_u64 v[82:83], v[82:83], 0, s[8:9]
	s_waitcnt lgkmcnt(0)
	v_add_f32_e32 v80, v80, v81
	flat_store_dword v[82:83], v80
.LBB0_310:
	s_or_b64 exec, exec, s[18:19]
	v_or_b32_e32 v88, 32, v120
	v_ashrrev_i32_e32 v89, 31, v88
	s_waitcnt lgkmcnt(0)
	v_lshlrev_b64 v[80:81], 11, v[88:89]
	v_lshl_add_u64 v[80:81], s[26:27], 0, v[80:81]
	v_lshl_add_u64 v[90:91], v[80:81], 0, v[186:187]
	global_load_dwordx4 v[84:87], v[90:91], off
	global_load_dwordx4 v[80:83], v[90:91], off offset:256
	v_lshlrev_b32_e32 v92, 16, v132
	v_fmac_f32_e32 v92, 0.5, v76
	v_and_b32_e32 v76, 0xffff0000, v132
	v_fmac_f32_e32 v76, 0.5, v77
	v_lshlrev_b32_e32 v77, 16, v133
	v_fmac_f32_e32 v77, 0.5, v78
	v_and_b32_e32 v78, 0xffff0000, v133
	v_fmac_f32_e32 v78, 0.5, v79
	v_lshlrev_b32_e32 v79, 16, v134
	v_and_b32_e32 v93, 0xffff0000, v134
	v_fmac_f32_e32 v79, 0.5, v72
	v_fmac_f32_e32 v93, 0.5, v73
	v_cvt_pk_bf16_f32 v72, v92, v76
	v_cvt_pk_bf16_f32 v73, v77, v78
	v_mul_f32_e32 v76, v76, v76
	v_mul_f32_e32 v78, v78, v78
	v_and_b32_e32 v95, 0xffff0000, v135
	v_fmac_f32_e32 v76, v92, v92
	v_fmac_f32_e32 v78, v77, v77
	v_mul_f32_e32 v77, v93, v93
	v_lshlrev_b32_e32 v94, 16, v135
	v_fmac_f32_e32 v95, 0.5, v75
	v_add_f32_e32 v76, v76, v78
	v_fmac_f32_e32 v77, v79, v79
	v_fmac_f32_e32 v94, 0.5, v74
	v_add_f32_e32 v76, v77, v76
	v_mul_f32_e32 v77, v95, v95
	v_fmac_f32_e32 v77, v94, v94
	v_add_f32_e32 v76, v77, v76
	v_lshlrev_b32_e32 v77, 16, v128
	v_fmac_f32_e32 v77, 0.5, v68
	v_and_b32_e32 v68, 0xffff0000, v128
	v_and_b32_e32 v78, 0xffff0000, v129
	v_cvt_pk_bf16_f32 v74, v79, v93
	v_fmac_f32_e32 v68, 0.5, v69
	v_lshlrev_b32_e32 v69, 16, v129
	v_fmac_f32_e32 v78, 0.5, v71
	v_lshlrev_b32_e32 v79, 16, v130
	v_and_b32_e32 v92, 0xffff0000, v130
	v_fmac_f32_e32 v69, 0.5, v70
	v_fmac_f32_e32 v79, 0.5, v64
	v_fmac_f32_e32 v92, 0.5, v65
	v_mul_f32_e32 v64, v68, v68
	v_mul_f32_e32 v65, v78, v78
	v_fmac_f32_e32 v64, v77, v77
	v_fmac_f32_e32 v65, v69, v69
	v_cvt_pk_bf16_f32 v75, v94, v95
	v_and_b32_e32 v94, 0xffff0000, v131
	v_add_f32_e32 v64, v64, v65
	v_mul_f32_e32 v65, v92, v92
	v_lshlrev_b32_e32 v93, 16, v131
	v_fmac_f32_e32 v94, 0.5, v67
	v_fmac_f32_e32 v65, v79, v79
	v_fmac_f32_e32 v93, 0.5, v66
	v_add_f32_e32 v64, v65, v64
	v_mul_f32_e32 v65, v94, v94
	v_fmac_f32_e32 v65, v93, v93
	v_add_f32_e32 v64, v65, v64
	v_add_f32_e32 v67, v76, v64
	v_mov_b32_e32 v76, v67
	s_nop 1
	v_permlane16_swap_b32 v67, v76
	v_lshl_add_u64 v[64:65], s[26:27], 0, v[190:191]
	v_lshl_add_u64 v[70:71], v[64:65], 0, v[186:187]
	global_store_dwordx4 v[70:71], v[72:75], off
	v_cvt_pk_bf16_f32 v66, v77, v68
	s_waitcnt lgkmcnt(0)
	v_add_f32_e32 v64, v67, v76
	v_mov_b32_e32 v65, v64
	s_nop 1
	v_permlane32_swap_b32 v64, v65
	v_cvt_pk_bf16_f32 v67, v69, v78
	v_cvt_pk_bf16_f32 v68, v79, v92
	v_cvt_pk_bf16_f32 v69, v93, v94
	global_store_dwordx4 v[70:71], v[66:69], off offset:256
	s_and_saveexec_b64 s[18:19], s[46:47]
	s_cbranch_execz .LBB0_312
	v_lshlrev_b64 v[66:67], 6, v[188:189]
	v_lshl_add_u64 v[66:67], s[28:29], 0, v[66:67]
	v_lshl_add_u64 v[66:67], s[60:61], 2, v[66:67]
	s_lshl_b32 s8, s78, 2
	v_lshl_add_u64 v[66:67], v[66:67], 0, s[8:9]
	s_waitcnt lgkmcnt(0)
	v_add_f32_e32 v64, v64, v65
	flat_store_dword v[66:67], v64
.LBB0_312:
	s_or_b64 exec, exec, s[18:19]
	v_or_b32_e32 v72, 48, v120
	v_ashrrev_i32_e32 v73, 31, v72
	s_waitcnt lgkmcnt(0)
	v_lshlrev_b64 v[64:65], 11, v[72:73]
	v_lshl_add_u64 v[64:65], s[26:27], 0, v[64:65]
	v_lshl_add_u64 v[74:75], v[182:183], 1, v[64:65]
	global_load_dwordx4 v[68:71], v[74:75], off
	global_load_dwordx4 v[64:67], v[74:75], off offset:256
	s_waitcnt vmcnt(15)
	v_lshlrev_b32_e32 v76, 16, v116
	v_fmac_f32_e32 v76, 0.5, v60
	v_and_b32_e32 v60, 0xffff0000, v116
	v_fmac_f32_e32 v60, 0.5, v61
	v_lshlrev_b32_e32 v61, 16, v117
	v_fmac_f32_e32 v61, 0.5, v62
	v_and_b32_e32 v62, 0xffff0000, v117
	v_fmac_f32_e32 v62, 0.5, v63
	v_lshlrev_b32_e32 v63, 16, v118
	v_lshlrev_b32_e32 v78, 16, v119
	v_fmac_f32_e32 v63, 0.5, v56
	v_fmac_f32_e32 v78, 0.5, v58
	v_cvt_pk_bf16_f32 v56, v76, v60
	v_mul_f32_e32 v58, v60, v60
	v_lshlrev_b32_e32 v60, 16, v112
	v_fmac_f32_e32 v60, 0.5, v52
	v_and_b32_e32 v52, 0xffff0000, v112
	v_and_b32_e32 v79, 0xffff0000, v119
	v_fmac_f32_e32 v52, 0.5, v53
	v_lshlrev_b32_e32 v53, 16, v113
	v_and_b32_e32 v77, 0xffff0000, v118
	v_fmac_f32_e32 v79, 0.5, v59
	v_mul_f32_e32 v59, v62, v62
	v_fmac_f32_e32 v53, 0.5, v54
	v_and_b32_e32 v54, 0xffff0000, v113
	v_fmac_f32_e32 v77, 0.5, v57
	v_cvt_pk_bf16_f32 v57, v61, v62
	v_fmac_f32_e32 v59, v61, v61
	v_fmac_f32_e32 v54, 0.5, v55
	v_lshlrev_b32_e32 v55, 16, v114
	v_and_b32_e32 v61, 0xffff0000, v114
	v_fmac_f32_e32 v55, 0.5, v48
	v_fmac_f32_e32 v61, 0.5, v49
	v_mul_f32_e32 v48, v52, v52
	v_mul_f32_e32 v49, v54, v54
	v_fmac_f32_e32 v58, v76, v76
	v_fmac_f32_e32 v48, v60, v60
	v_fmac_f32_e32 v49, v53, v53
	v_add_f32_e32 v58, v58, v59
	v_mul_f32_e32 v59, v77, v77
	v_and_b32_e32 v76, 0xffff0000, v115
	v_add_f32_e32 v48, v48, v49
	v_mul_f32_e32 v49, v61, v61
	v_fmac_f32_e32 v59, v63, v63
	v_lshlrev_b32_e32 v62, 16, v115
	v_fmac_f32_e32 v76, 0.5, v51
	v_fmac_f32_e32 v49, v55, v55
	v_add_f32_e32 v58, v59, v58
	v_mul_f32_e32 v59, v79, v79
	v_fmac_f32_e32 v62, 0.5, v50
	v_add_f32_e32 v48, v49, v48
	v_mul_f32_e32 v49, v76, v76
	v_fmac_f32_e32 v59, v78, v78
	v_fmac_f32_e32 v49, v62, v62
	v_add_f32_e32 v58, v59, v58
	v_add_f32_e32 v48, v49, v48
	v_add_f32_e32 v48, v58, v48
	v_mov_b32_e32 v49, v48
	s_nop 1
	v_permlane16_swap_b32 v48, v49
	v_cvt_pk_bf16_f32 v58, v63, v77
	v_cvt_pk_bf16_f32 v59, v78, v79
	global_store_dwordx4 v[122:123], v[56:59], off
	v_cvt_pk_bf16_f32 v50, v60, v52
	s_waitcnt lgkmcnt(0)
	v_add_f32_e32 v48, v48, v49
	v_mov_b32_e32 v49, v48
	s_nop 1
	v_permlane32_swap_b32 v48, v49
	v_cvt_pk_bf16_f32 v51, v53, v54
	v_cvt_pk_bf16_f32 v52, v55, v61
	v_cvt_pk_bf16_f32 v53, v62, v76
	global_store_dwordx4 v[122:123], v[50:53], off offset:256
	s_and_saveexec_b64 s[18:19], s[46:47]
	s_cbranch_execz .LBB0_314
	v_lshlrev_b64 v[50:51], 6, v[120:121]
	v_lshl_add_u64 v[50:51], s[28:29], 0, v[50:51]
	v_lshl_add_u64 v[50:51], s[60:61], 2, v[50:51]
	s_lshl_b32 s8, s78, 2
	v_lshl_add_u64 v[50:51], v[50:51], 0, s[8:9]
	s_waitcnt lgkmcnt(0)
	v_add_f32_e32 v48, v48, v49
	flat_store_dword v[50:51], v48
.LBB0_314:
	s_or_b64 exec, exec, s[18:19]
	s_waitcnt vmcnt(13)
	v_lshlrev_b32_e32 v48, 16, v100
	v_fmac_f32_e32 v48, 0.5, v44
	v_and_b32_e32 v44, 0xffff0000, v100
	v_fmac_f32_e32 v44, 0.5, v45
	v_lshlrev_b32_e32 v45, 16, v101
	v_fmac_f32_e32 v45, 0.5, v46
	v_and_b32_e32 v46, 0xffff0000, v101
	v_fmac_f32_e32 v46, 0.5, v47
	v_lshlrev_b32_e32 v47, 16, v102
	v_lshlrev_b32_e32 v50, 16, v103
	v_fmac_f32_e32 v47, 0.5, v40
	v_fmac_f32_e32 v50, 0.5, v42
	v_cvt_pk_bf16_f32 v40, v48, v44
	v_mul_f32_e32 v42, v44, v44
	v_lshlrev_b32_e32 v44, 16, v96
	v_fmac_f32_e32 v44, 0.5, v36
	v_and_b32_e32 v36, 0xffff0000, v96
	v_and_b32_e32 v51, 0xffff0000, v103
	v_fmac_f32_e32 v36, 0.5, v37
	v_lshlrev_b32_e32 v37, 16, v97
	s_waitcnt lgkmcnt(0)
	v_and_b32_e32 v49, 0xffff0000, v102
	v_fmac_f32_e32 v51, 0.5, v43
	v_mul_f32_e32 v43, v46, v46
	v_fmac_f32_e32 v37, 0.5, v38
	v_and_b32_e32 v38, 0xffff0000, v97
	v_fmac_f32_e32 v49, 0.5, v41
	v_cvt_pk_bf16_f32 v41, v45, v46
	v_fmac_f32_e32 v43, v45, v45
	v_fmac_f32_e32 v38, 0.5, v39
	v_lshlrev_b32_e32 v39, 16, v98
	v_and_b32_e32 v45, 0xffff0000, v98
	v_fmac_f32_e32 v39, 0.5, v32
	v_fmac_f32_e32 v45, 0.5, v33
	v_mul_f32_e32 v32, v36, v36
	v_mul_f32_e32 v33, v38, v38
	v_fmac_f32_e32 v42, v48, v48
	v_fmac_f32_e32 v32, v44, v44
	v_fmac_f32_e32 v33, v37, v37
	v_add_f32_e32 v42, v42, v43
	v_mul_f32_e32 v43, v49, v49
	v_and_b32_e32 v48, 0xffff0000, v99
	v_add_f32_e32 v32, v32, v33
	v_mul_f32_e32 v33, v45, v45
	v_fmac_f32_e32 v43, v47, v47
	v_lshlrev_b32_e32 v46, 16, v99
	v_fmac_f32_e32 v48, 0.5, v35
	v_fmac_f32_e32 v33, v39, v39
	v_add_f32_e32 v42, v43, v42
	v_mul_f32_e32 v43, v51, v51
	v_fmac_f32_e32 v46, 0.5, v34
	v_add_f32_e32 v32, v33, v32
	v_mul_f32_e32 v33, v48, v48
	v_fmac_f32_e32 v43, v50, v50
	v_fmac_f32_e32 v33, v46, v46
	v_add_f32_e32 v42, v43, v42
	v_add_f32_e32 v32, v33, v32
	v_add_f32_e32 v32, v42, v32
	v_mov_b32_e32 v33, v32
	s_nop 1
	v_permlane16_swap_b32 v32, v33
	v_cvt_pk_bf16_f32 v42, v47, v49
	v_cvt_pk_bf16_f32 v43, v50, v51
	global_store_dwordx4 v[106:107], v[40:43], off
	v_cvt_pk_bf16_f32 v34, v44, v36
	s_waitcnt lgkmcnt(0)
	v_add_f32_e32 v32, v32, v33
	v_mov_b32_e32 v33, v32
	s_nop 1
	v_permlane32_swap_b32 v32, v33
	v_cvt_pk_bf16_f32 v35, v37, v38
	v_cvt_pk_bf16_f32 v36, v39, v45
	v_cvt_pk_bf16_f32 v37, v46, v48
	global_store_dwordx4 v[106:107], v[34:37], off offset:256
	s_and_saveexec_b64 s[18:19], s[46:47]
	s_cbranch_execz .LBB0_316
	v_lshlrev_b64 v[34:35], 6, v[104:105]
	v_lshl_add_u64 v[34:35], s[28:29], 0, v[34:35]
	v_lshl_add_u64 v[34:35], s[60:61], 2, v[34:35]
	s_lshl_b32 s8, s78, 2
	v_lshl_add_u64 v[34:35], v[34:35], 0, s[8:9]
	s_waitcnt lgkmcnt(0)
	v_add_f32_e32 v32, v32, v33
	flat_store_dword v[34:35], v32
.LBB0_316:
	s_or_b64 exec, exec, s[18:19]
	s_waitcnt vmcnt(11)
	v_lshlrev_b32_e32 v32, 16, v84
	v_fmac_f32_e32 v32, 0.5, v28
	v_and_b32_e32 v28, 0xffff0000, v84
	v_fmac_f32_e32 v28, 0.5, v29
	v_lshlrev_b32_e32 v29, 16, v85
	v_fmac_f32_e32 v29, 0.5, v30
	v_and_b32_e32 v30, 0xffff0000, v85
	v_fmac_f32_e32 v30, 0.5, v31
	v_lshlrev_b32_e32 v31, 16, v86
	v_lshlrev_b32_e32 v34, 16, v87
	v_fmac_f32_e32 v31, 0.5, v24
	v_fmac_f32_e32 v34, 0.5, v26
	v_cvt_pk_bf16_f32 v24, v32, v28
	v_mul_f32_e32 v26, v28, v28
	v_lshlrev_b32_e32 v28, 16, v80
	v_fmac_f32_e32 v28, 0.5, v20
	v_and_b32_e32 v20, 0xffff0000, v80
	v_and_b32_e32 v35, 0xffff0000, v87
	v_fmac_f32_e32 v20, 0.5, v21
	v_lshlrev_b32_e32 v21, 16, v81
	s_waitcnt lgkmcnt(0)
	v_and_b32_e32 v33, 0xffff0000, v86
	v_fmac_f32_e32 v35, 0.5, v27
	v_mul_f32_e32 v27, v30, v30
	v_fmac_f32_e32 v21, 0.5, v22
	v_and_b32_e32 v22, 0xffff0000, v81
	v_fmac_f32_e32 v33, 0.5, v25
	v_cvt_pk_bf16_f32 v25, v29, v30
	v_fmac_f32_e32 v27, v29, v29
	v_fmac_f32_e32 v22, 0.5, v23
	v_lshlrev_b32_e32 v23, 16, v82
	v_and_b32_e32 v29, 0xffff0000, v82
	v_fmac_f32_e32 v23, 0.5, v16
	v_fmac_f32_e32 v29, 0.5, v17
	v_mul_f32_e32 v16, v20, v20
	v_mul_f32_e32 v17, v22, v22
	v_fmac_f32_e32 v26, v32, v32
	v_fmac_f32_e32 v16, v28, v28
	v_fmac_f32_e32 v17, v21, v21
	v_add_f32_e32 v26, v26, v27
	v_mul_f32_e32 v27, v33, v33
	v_and_b32_e32 v32, 0xffff0000, v83
	v_add_f32_e32 v16, v16, v17
	v_mul_f32_e32 v17, v29, v29
	v_fmac_f32_e32 v27, v31, v31
	v_lshlrev_b32_e32 v30, 16, v83
	v_fmac_f32_e32 v32, 0.5, v19
	v_fmac_f32_e32 v17, v23, v23
	v_add_f32_e32 v26, v27, v26
	v_mul_f32_e32 v27, v35, v35
	v_fmac_f32_e32 v30, 0.5, v18
	v_add_f32_e32 v16, v17, v16
	v_mul_f32_e32 v17, v32, v32
	v_fmac_f32_e32 v27, v34, v34
	v_fmac_f32_e32 v17, v30, v30
	v_add_f32_e32 v26, v27, v26
	v_add_f32_e32 v16, v17, v16
	v_add_f32_e32 v16, v26, v16
	v_mov_b32_e32 v17, v16
	s_nop 1
	v_permlane16_swap_b32 v16, v17
	v_cvt_pk_bf16_f32 v26, v31, v33
	v_cvt_pk_bf16_f32 v27, v34, v35
	global_store_dwordx4 v[90:91], v[24:27], off
	v_cvt_pk_bf16_f32 v18, v28, v20
	s_waitcnt lgkmcnt(0)
	v_add_f32_e32 v16, v16, v17
	v_mov_b32_e32 v17, v16
	s_nop 1
	v_permlane32_swap_b32 v16, v17
	v_cvt_pk_bf16_f32 v19, v21, v22
	v_cvt_pk_bf16_f32 v20, v23, v29
	v_cvt_pk_bf16_f32 v21, v30, v32
	global_store_dwordx4 v[90:91], v[18:21], off offset:256
	s_and_saveexec_b64 s[18:19], s[46:47]
	s_cbranch_execz .LBB0_318
	v_lshlrev_b64 v[18:19], 6, v[88:89]
	v_lshl_add_u64 v[18:19], s[28:29], 0, v[18:19]
	v_lshl_add_u64 v[18:19], s[60:61], 2, v[18:19]
	s_lshl_b32 s8, s78, 2
	v_lshl_add_u64 v[18:19], v[18:19], 0, s[8:9]
	s_waitcnt lgkmcnt(0)
	v_add_f32_e32 v16, v16, v17
	flat_store_dword v[18:19], v16
.LBB0_318:
	s_or_b64 exec, exec, s[18:19]
	s_waitcnt vmcnt(9)
	v_lshlrev_b32_e32 v16, 16, v68
	v_fmac_f32_e32 v16, 0.5, v12
	v_and_b32_e32 v12, 0xffff0000, v68
	v_fmac_f32_e32 v12, 0.5, v13
	v_lshlrev_b32_e32 v13, 16, v69
	v_fmac_f32_e32 v13, 0.5, v14
	v_and_b32_e32 v14, 0xffff0000, v69
	v_fmac_f32_e32 v14, 0.5, v15
	v_lshlrev_b32_e32 v15, 16, v70
	v_lshlrev_b32_e32 v18, 16, v71
	v_fmac_f32_e32 v15, 0.5, v8
	v_fmac_f32_e32 v18, 0.5, v10
	v_cvt_pk_bf16_f32 v8, v16, v12
	v_mul_f32_e32 v10, v12, v12
	v_lshlrev_b32_e32 v12, 16, v64
	v_fmac_f32_e32 v12, 0.5, v4
	v_and_b32_e32 v4, 0xffff0000, v64
	v_and_b32_e32 v19, 0xffff0000, v71
	v_fmac_f32_e32 v4, 0.5, v5
	v_lshlrev_b32_e32 v5, 16, v65
	s_waitcnt lgkmcnt(0)
	v_and_b32_e32 v17, 0xffff0000, v70
	v_fmac_f32_e32 v19, 0.5, v11
	v_mul_f32_e32 v11, v14, v14
	v_fmac_f32_e32 v5, 0.5, v6
	v_and_b32_e32 v6, 0xffff0000, v65
	v_fmac_f32_e32 v17, 0.5, v9
	v_cvt_pk_bf16_f32 v9, v13, v14
	v_fmac_f32_e32 v11, v13, v13
	v_fmac_f32_e32 v6, 0.5, v7
	v_lshlrev_b32_e32 v7, 16, v66
	v_and_b32_e32 v13, 0xffff0000, v66
	v_fmac_f32_e32 v7, 0.5, v0
	v_fmac_f32_e32 v13, 0.5, v1
	v_mul_f32_e32 v0, v4, v4
	v_mul_f32_e32 v1, v6, v6
	v_fmac_f32_e32 v10, v16, v16
	v_fmac_f32_e32 v0, v12, v12
	v_fmac_f32_e32 v1, v5, v5
	v_add_f32_e32 v10, v10, v11
	v_mul_f32_e32 v11, v17, v17
	v_and_b32_e32 v16, 0xffff0000, v67
	v_add_f32_e32 v0, v0, v1
	v_mul_f32_e32 v1, v13, v13
	v_fmac_f32_e32 v11, v15, v15
	v_lshlrev_b32_e32 v14, 16, v67
	v_fmac_f32_e32 v16, 0.5, v3
	v_fmac_f32_e32 v1, v7, v7
	v_add_f32_e32 v10, v11, v10
	v_mul_f32_e32 v11, v19, v19
	v_fmac_f32_e32 v14, 0.5, v2
	v_add_f32_e32 v0, v1, v0
	v_mul_f32_e32 v1, v16, v16
	v_fmac_f32_e32 v11, v18, v18
	v_fmac_f32_e32 v1, v14, v14
	v_add_f32_e32 v10, v11, v10
	v_add_f32_e32 v0, v1, v0
	v_add_f32_e32 v0, v10, v0
	v_mov_b32_e32 v1, v0
	s_nop 1
	v_permlane16_swap_b32 v0, v1
	v_cvt_pk_bf16_f32 v10, v15, v17
	v_cvt_pk_bf16_f32 v11, v18, v19
	global_store_dwordx4 v[74:75], v[8:11], off
	v_cvt_pk_bf16_f32 v2, v12, v4
	s_waitcnt lgkmcnt(0)
	v_add_f32_e32 v0, v0, v1
	v_mov_b32_e32 v1, v0
	s_nop 1
	v_permlane32_swap_b32 v0, v1
	v_cvt_pk_bf16_f32 v3, v5, v6
	v_cvt_pk_bf16_f32 v4, v7, v13
	v_cvt_pk_bf16_f32 v5, v14, v16
	global_store_dwordx4 v[74:75], v[2:5], off offset:256
	s_and_saveexec_b64 s[18:19], s[46:47]
	s_cbranch_execz .LBB0_320
	v_lshlrev_b64 v[2:3], 6, v[72:73]
	v_lshl_add_u64 v[2:3], s[28:29], 0, v[2:3]
	v_lshl_add_u64 v[2:3], s[60:61], 2, v[2:3]
	s_lshl_b32 s8, s78, 2
	v_lshl_add_u64 v[2:3], v[2:3], 0, s[8:9]
	s_waitcnt lgkmcnt(0)
	v_add_f32_e32 v0, v0, v1
	flat_store_dword v[2:3], v0

.LBB0_825:
	v_lshl_or_b32 v182, s8, 8, v211
	v_lshl_add_u32 v198, s80, 8, v209
	v_ashrrev_i32_e32 v183, 31, v182
	v_ashrrev_i32_e32 v199, 31, v198
	v_lshlrev_b64 v[184:185], 1, v[182:183]
	v_lshl_add_u64 v[112:113], s[26:27], 0, v[184:185]
	v_lshlrev_b64 v[224:225], 11, v[198:199]
	v_lshl_add_u64 v[114:115], v[112:113], 0, v[224:225]
	global_load_dwordx4 v[214:217], v[114:115], off
	global_load_dwordx4 v[218:221], v[114:115], off offset:256
	v_or_b32_e32 v194, 16, v198
	v_ashrrev_i32_e32 v195, 31, v194
	v_or_b32_e32 v190, 32, v198
	v_or_b32_e32 v186, 48, v198
	v_lshlrev_b64 v[196:197], 11, v[194:195]
	v_ashrrev_i32_e32 v191, 31, v190
	v_ashrrev_i32_e32 v187, 31, v186
	v_lshl_add_u64 v[114:115], v[112:113], 0, v[196:197]
	v_lshlrev_b64 v[192:193], 11, v[190:191]
	v_lshlrev_b64 v[188:189], 11, v[186:187]
	global_load_dwordx4 v[140:143], v[114:115], off
	global_load_dwordx4 v[132:135], v[114:115], off offset:256
	v_lshl_add_u64 v[114:115], v[112:113], 0, v[192:193]
	v_lshl_add_u64 v[112:113], v[112:113], 0, v[188:189]
	global_load_dwordx4 v[124:127], v[114:115], off
	global_load_dwordx4 v[120:123], v[114:115], off offset:256
	global_load_dwordx4 v[116:119], v[112:113], off
	s_nop 0
	global_load_dwordx4 v[112:115], v[112:113], off offset:256
	s_lshl_b32 s60, s8, 2
	s_ashr_i32 s61, s60, 31
	s_waitcnt vmcnt(0)
	v_lshlrev_b32_e32 v213, 16, v214
	v_add_f32_e32 v213, v148, v213
	v_and_b32_e32 v148, 0xffff0000, v214
	v_add_f32_e32 v214, v149, v148
	v_lshlrev_b32_e32 v148, 16, v215
	v_add_f32_e32 v150, v150, v148
	v_and_b32_e32 v148, 0xffff0000, v215
	v_add_f32_e32 v151, v151, v148
	v_lshlrev_b32_e32 v148, 16, v216
	v_add_f32_e32 v215, v144, v148
	v_and_b32_e32 v144, 0xffff0000, v216
	v_add_f32_e32 v216, v145, v144
	v_lshlrev_b32_e32 v144, 16, v217
	v_add_f32_e32 v226, v146, v144
	v_and_b32_e32 v144, 0xffff0000, v217
	v_lshl_add_u64 v[148:149], s[26:27], 0, v[224:225]
	v_add_f32_e32 v217, v147, v144
	v_cvt_pk_bf16_f32 v144, v213, v214
	v_cvt_pk_bf16_f32 v145, v150, v151
	v_lshl_add_u64 v[148:149], v[148:149], 0, v[184:185]
	v_cvt_pk_bf16_f32 v146, v215, v216
	v_cvt_pk_bf16_f32 v147, v226, v217
	global_store_dwordx4 v[148:149], v[144:147], off
	s_nop 1
	v_mul_f32_e32 v144, v214, v214
	v_mul_f32_e32 v145, v151, v151
	v_fmac_f32_e32 v144, v213, v213
	v_fmac_f32_e32 v145, v150, v150
	v_add_f32_e32 v144, v144, v145
	v_mul_f32_e32 v145, v216, v216
	v_fmac_f32_e32 v145, v215, v215
	v_add_f32_e32 v144, v145, v144
	v_mul_f32_e32 v145, v217, v217
	v_fmac_f32_e32 v145, v226, v226
	v_add_f32_e32 v144, v145, v144
	v_lshlrev_b32_e32 v145, 16, v218
	v_add_f32_e32 v136, v136, v145
	v_and_b32_e32 v145, 0xffff0000, v218
	v_add_f32_e32 v137, v137, v145
	v_lshlrev_b32_e32 v145, 16, v219
	v_add_f32_e32 v138, v138, v145
	v_and_b32_e32 v145, 0xffff0000, v219
	v_add_f32_e32 v139, v139, v145
	v_lshlrev_b32_e32 v145, 16, v220
	v_add_f32_e32 v145, v128, v145
	v_and_b32_e32 v128, 0xffff0000, v220
	v_add_f32_e32 v146, v129, v128
	v_lshlrev_b32_e32 v128, 16, v221
	v_add_f32_e32 v147, v130, v128
	v_and_b32_e32 v128, 0xffff0000, v221
	v_add_f32_e32 v150, v131, v128
	v_cvt_pk_bf16_f32 v128, v136, v137
	v_cvt_pk_bf16_f32 v129, v138, v139
	v_cvt_pk_bf16_f32 v130, v145, v146
	v_cvt_pk_bf16_f32 v131, v147, v150
	global_store_dwordx4 v[148:149], v[128:131], off offset:256
	s_nop 1
	v_mul_f32_e32 v128, v137, v137
	v_mul_f32_e32 v129, v139, v139
	v_fmac_f32_e32 v128, v136, v136
	v_fmac_f32_e32 v129, v138, v138
	v_add_f32_e32 v128, v128, v129
	v_mul_f32_e32 v129, v146, v146
	v_fmac_f32_e32 v129, v145, v145
	v_add_f32_e32 v128, v129, v128
	v_mul_f32_e32 v129, v150, v150
	v_fmac_f32_e32 v129, v147, v147
	v_add_f32_e32 v128, v129, v128
	v_xor_b32_e32 v129, 16, v204
	v_cmp_lt_i32_e32 vcc, v129, v205
	v_add_f32_e32 v128, v144, v128
	s_nop 0
	v_cndmask_b32_e32 v129, v204, v129, vcc
	v_lshlrev_b32_e32 v148, 2, v129
	v_mov_b32_e32 v129, v128
	s_nop 1
	v_permlane16_swap_b32 v128, v129
	s_waitcnt lgkmcnt(0)
	v_add_f32_e32 v128, v128, v129
	v_xor_b32_e32 v129, 32, v204
	v_cmp_lt_i32_e32 vcc, v129, v205
	s_nop 1
	v_cndmask_b32_e32 v129, v204, v129, vcc
	v_lshlrev_b32_e32 v149, 2, v129
	v_mov_b32_e32 v129, v128
	s_nop 1
	v_permlane32_swap_b32 v128, v129
	s_and_saveexec_b64 s[62:63], s[44:45]
	s_cbranch_execz .LBB0_827
	v_lshlrev_b64 v[130:131], 6, v[198:199]
	v_lshl_add_u64 v[130:131], s[28:29], 0, v[130:131]
	v_lshl_add_u64 v[130:131], s[60:61], 2, v[130:131]
	s_lshl_b32 s8, s76, 2
	v_lshl_add_u64 v[130:131], v[130:131], 0, s[8:9]
	s_waitcnt lgkmcnt(0)
	v_add_f32_e32 v128, v128, v129
	flat_store_dword v[130:131], v128
.LBB0_827:
	s_or_b64 exec, exec, s[62:63]
	v_add_u32_e32 v144, 0x80, v198
	v_ashrrev_i32_e32 v145, 31, v144
	s_waitcnt lgkmcnt(0)
	v_lshlrev_b64 v[128:129], 11, v[144:145]
	v_lshl_add_u64 v[128:129], s[26:27], 0, v[128:129]
	v_lshl_add_u64 v[146:147], v[128:129], 0, v[184:185]
	global_load_dwordx4 v[136:139], v[146:147], off
	global_load_dwordx4 v[128:131], v[146:147], off offset:256
	v_lshlrev_b32_e32 v150, 16, v140
	v_and_b32_e32 v140, 0xffff0000, v140
	v_add_f32_e32 v109, v109, v140
	v_lshlrev_b32_e32 v140, 16, v141
	v_add_f32_e32 v110, v110, v140
	v_and_b32_e32 v140, 0xffff0000, v141
	v_add_f32_e32 v111, v111, v140
	v_lshlrev_b32_e32 v140, 16, v142
	v_add_f32_e32 v140, v104, v140
	v_and_b32_e32 v104, 0xffff0000, v142
	v_add_f32_e32 v141, v105, v104
	v_lshlrev_b32_e32 v104, 16, v143
	v_add_f32_e32 v142, v106, v104
	v_and_b32_e32 v104, 0xffff0000, v143
	v_add_f32_e32 v108, v108, v150
	v_add_f32_e32 v143, v107, v104
	v_cvt_pk_bf16_f32 v104, v108, v109
	v_mul_f32_e32 v109, v109, v109
	v_fmac_f32_e32 v109, v108, v108
	v_mul_f32_e32 v108, v111, v111
	v_fmac_f32_e32 v108, v110, v110
	v_add_f32_e32 v108, v109, v108
	v_mul_f32_e32 v109, v141, v141
	v_fmac_f32_e32 v109, v140, v140
	v_add_f32_e32 v108, v109, v108
	v_mul_f32_e32 v109, v143, v143
	v_fmac_f32_e32 v109, v142, v142
	v_add_f32_e32 v108, v109, v108
	v_lshlrev_b32_e32 v109, 16, v132
	v_add_f32_e32 v100, v100, v109
	v_and_b32_e32 v109, 0xffff0000, v132
	v_add_f32_e32 v101, v101, v109
	v_lshlrev_b32_e32 v109, 16, v133
	v_add_f32_e32 v109, v102, v109
	v_and_b32_e32 v102, 0xffff0000, v133
	v_cvt_pk_bf16_f32 v105, v110, v111
	v_add_f32_e32 v110, v103, v102
	v_lshlrev_b32_e32 v102, 16, v134
	v_add_f32_e32 v111, v96, v102
	v_and_b32_e32 v96, 0xffff0000, v134
	v_add_f32_e32 v132, v97, v96
	v_lshlrev_b32_e32 v96, 16, v135
	v_add_f32_e32 v133, v98, v96
	v_and_b32_e32 v96, 0xffff0000, v135
	v_add_f32_e32 v134, v99, v96
	v_mul_f32_e32 v96, v101, v101
	v_mul_f32_e32 v97, v110, v110
	v_fmac_f32_e32 v96, v100, v100
	v_fmac_f32_e32 v97, v109, v109
	v_add_f32_e32 v96, v96, v97
	v_mul_f32_e32 v97, v132, v132
	v_fmac_f32_e32 v97, v111, v111
	v_add_f32_e32 v96, v97, v96
	v_mul_f32_e32 v97, v134, v134
	v_fmac_f32_e32 v97, v133, v133
	v_add_f32_e32 v96, v97, v96
	v_add_f32_e32 v99, v108, v96
	v_mov_b32_e32 v108, v99
	s_nop 1
	v_permlane16_swap_b32 v99, v108
	v_lshl_add_u64 v[96:97], s[26:27], 0, v[196:197]
	v_lshl_add_u64 v[102:103], v[96:97], 0, v[184:185]
	v_cvt_pk_bf16_f32 v106, v140, v141
	v_cvt_pk_bf16_f32 v107, v142, v143
	s_waitcnt lgkmcnt(0)
	v_add_f32_e32 v96, v99, v108
	v_mov_b32_e32 v97, v96
	s_nop 1
	v_permlane32_swap_b32 v96, v97
	global_store_dwordx4 v[102:103], v[104:107], off
	v_cvt_pk_bf16_f32 v98, v100, v101
	v_cvt_pk_bf16_f32 v99, v109, v110
	v_cvt_pk_bf16_f32 v100, v111, v132
	v_cvt_pk_bf16_f32 v101, v133, v134
	global_store_dwordx4 v[102:103], v[98:101], off offset:256
	s_and_saveexec_b64 s[62:63], s[44:45]
	s_cbranch_execz .LBB0_829
	v_lshlrev_b64 v[98:99], 6, v[194:195]
	v_lshl_add_u64 v[98:99], s[28:29], 0, v[98:99]
	v_lshl_add_u64 v[98:99], s[60:61], 2, v[98:99]
	s_lshl_b32 s8, s76, 2
	v_lshl_add_u64 v[98:99], v[98:99], 0, s[8:9]
	s_waitcnt lgkmcnt(0)
	v_add_f32_e32 v96, v96, v97
	flat_store_dword v[98:99], v96
.LBB0_829:
	s_or_b64 exec, exec, s[62:63]
	v_or_b32_e32 v104, 16, v144
	v_ashrrev_i32_e32 v105, 31, v104
	s_waitcnt lgkmcnt(0)
	v_lshlrev_b64 v[96:97], 11, v[104:105]
	v_lshl_add_u64 v[96:97], s[26:27], 0, v[96:97]
	v_lshl_add_u64 v[106:107], v[96:97], 0, v[184:185]
	global_load_dwordx4 v[100:103], v[106:107], off
	global_load_dwordx4 v[96:99], v[106:107], off offset:256
	v_lshlrev_b32_e32 v108, 16, v124
	v_add_f32_e32 v92, v92, v108
	v_and_b32_e32 v108, 0xffff0000, v124
	v_add_f32_e32 v93, v93, v108
	v_lshlrev_b32_e32 v108, 16, v125
	v_add_f32_e32 v94, v94, v108
	v_and_b32_e32 v108, 0xffff0000, v125
	v_add_f32_e32 v95, v95, v108
	v_lshlrev_b32_e32 v108, 16, v126
	v_add_f32_e32 v108, v88, v108
	v_and_b32_e32 v88, 0xffff0000, v126
	v_add_f32_e32 v109, v89, v88
	v_lshlrev_b32_e32 v88, 16, v127
	v_add_f32_e32 v110, v90, v88
	v_and_b32_e32 v88, 0xffff0000, v127
	v_add_f32_e32 v111, v91, v88
	v_cvt_pk_bf16_f32 v88, v92, v93
	v_mul_f32_e32 v93, v93, v93
	v_fmac_f32_e32 v93, v92, v92
	v_mul_f32_e32 v92, v95, v95
	v_fmac_f32_e32 v92, v94, v94
	v_add_f32_e32 v92, v93, v92
	v_mul_f32_e32 v93, v109, v109
	v_fmac_f32_e32 v93, v108, v108
	v_add_f32_e32 v92, v93, v92
	v_mul_f32_e32 v93, v111, v111
	v_fmac_f32_e32 v93, v110, v110
	v_add_f32_e32 v92, v93, v92
	v_lshlrev_b32_e32 v93, 16, v120
	v_add_f32_e32 v84, v84, v93
	v_and_b32_e32 v93, 0xffff0000, v120
	v_add_f32_e32 v85, v85, v93
	v_lshlrev_b32_e32 v93, 16, v121
	v_add_f32_e32 v93, v86, v93
	v_and_b32_e32 v86, 0xffff0000, v121
	v_cvt_pk_bf16_f32 v89, v94, v95
	v_add_f32_e32 v94, v87, v86
	v_lshlrev_b32_e32 v86, 16, v122
	v_add_f32_e32 v95, v80, v86
	v_and_b32_e32 v80, 0xffff0000, v122
	v_cvt_pk_bf16_f32 v90, v108, v109
	v_add_f32_e32 v108, v81, v80
	v_lshlrev_b32_e32 v80, 16, v123
	v_add_f32_e32 v109, v82, v80
	v_and_b32_e32 v80, 0xffff0000, v123
	v_cvt_pk_bf16_f32 v91, v110, v111
	v_add_f32_e32 v110, v83, v80
	v_mul_f32_e32 v80, v85, v85
	v_mul_f32_e32 v81, v94, v94
	v_fmac_f32_e32 v80, v84, v84
	v_fmac_f32_e32 v81, v93, v93
	v_add_f32_e32 v80, v80, v81
	v_mul_f32_e32 v81, v108, v108
	v_fmac_f32_e32 v81, v95, v95
	v_add_f32_e32 v80, v81, v80
	v_mul_f32_e32 v81, v110, v110
	v_fmac_f32_e32 v81, v109, v109
	v_add_f32_e32 v80, v81, v80
	v_add_f32_e32 v83, v92, v80
	v_mov_b32_e32 v92, v83
	s_nop 1
	v_permlane16_swap_b32 v83, v92
	v_lshl_add_u64 v[80:81], s[26:27], 0, v[192:193]
	v_lshl_add_u64 v[86:87], v[80:81], 0, v[184:185]
	global_store_dwordx4 v[86:87], v[88:91], off
	v_cvt_pk_bf16_f32 v82, v84, v85
	s_waitcnt lgkmcnt(0)
	v_add_f32_e32 v80, v83, v92
	v_mov_b32_e32 v81, v80
	s_nop 1
	v_permlane32_swap_b32 v80, v81
	v_cvt_pk_bf16_f32 v83, v93, v94
	v_cvt_pk_bf16_f32 v84, v95, v108
	v_cvt_pk_bf16_f32 v85, v109, v110
	global_store_dwordx4 v[86:87], v[82:85], off offset:256
	s_and_saveexec_b64 s[62:63], s[44:45]
	s_cbranch_execz .LBB0_831
	v_lshlrev_b64 v[82:83], 6, v[190:191]
	v_lshl_add_u64 v[82:83], s[28:29], 0, v[82:83]
	v_lshl_add_u64 v[82:83], s[60:61], 2, v[82:83]
	s_lshl_b32 s8, s76, 2
	v_lshl_add_u64 v[82:83], v[82:83], 0, s[8:9]
	s_waitcnt lgkmcnt(0)
	v_add_f32_e32 v80, v80, v81
	flat_store_dword v[82:83], v80
.LBB0_831:
	s_or_b64 exec, exec, s[62:63]
	v_or_b32_e32 v88, 32, v144
	v_ashrrev_i32_e32 v89, 31, v88
	s_waitcnt lgkmcnt(0)
	v_lshlrev_b64 v[80:81], 11, v[88:89]
	v_lshl_add_u64 v[80:81], s[26:27], 0, v[80:81]
	v_lshl_add_u64 v[90:91], v[80:81], 0, v[184:185]
	global_load_dwordx4 v[84:87], v[90:91], off
	global_load_dwordx4 v[80:83], v[90:91], off offset:256
	v_lshlrev_b32_e32 v92, 16, v116
	v_add_f32_e32 v76, v76, v92
	v_and_b32_e32 v92, 0xffff0000, v116
	v_add_f32_e32 v77, v77, v92
	v_lshlrev_b32_e32 v92, 16, v117
	v_add_f32_e32 v78, v78, v92
	v_and_b32_e32 v92, 0xffff0000, v117
	v_add_f32_e32 v79, v79, v92
	v_lshlrev_b32_e32 v92, 16, v118
	v_add_f32_e32 v92, v72, v92
	v_and_b32_e32 v72, 0xffff0000, v118
	v_add_f32_e32 v93, v73, v72
	v_lshlrev_b32_e32 v72, 16, v119
	v_add_f32_e32 v94, v74, v72
	v_and_b32_e32 v72, 0xffff0000, v119
	v_add_f32_e32 v95, v75, v72
	v_cvt_pk_bf16_f32 v72, v76, v77
	v_mul_f32_e32 v77, v77, v77
	v_fmac_f32_e32 v77, v76, v76
	v_mul_f32_e32 v76, v79, v79
	v_fmac_f32_e32 v76, v78, v78
	v_add_f32_e32 v76, v77, v76
	v_mul_f32_e32 v77, v93, v93
	v_fmac_f32_e32 v77, v92, v92
	v_add_f32_e32 v76, v77, v76
	v_mul_f32_e32 v77, v95, v95
	v_fmac_f32_e32 v77, v94, v94
	v_add_f32_e32 v76, v77, v76
	v_lshlrev_b32_e32 v77, 16, v112
	v_add_f32_e32 v68, v68, v77
	v_and_b32_e32 v77, 0xffff0000, v112
	v_add_f32_e32 v69, v69, v77
	v_lshlrev_b32_e32 v77, 16, v113
	v_add_f32_e32 v77, v70, v77
	v_and_b32_e32 v70, 0xffff0000, v113
	v_cvt_pk_bf16_f32 v73, v78, v79
	v_add_f32_e32 v78, v71, v70
	v_lshlrev_b32_e32 v70, 16, v114
	v_add_f32_e32 v79, v64, v70
	v_and_b32_e32 v64, 0xffff0000, v114
	v_cvt_pk_bf16_f32 v74, v92, v93
	v_add_f32_e32 v92, v65, v64
	v_lshlrev_b32_e32 v64, 16, v115
	v_add_f32_e32 v93, v66, v64
	v_and_b32_e32 v64, 0xffff0000, v115
	v_cvt_pk_bf16_f32 v75, v94, v95
	v_add_f32_e32 v94, v67, v64
	v_mul_f32_e32 v64, v69, v69
	v_mul_f32_e32 v65, v78, v78
	v_fmac_f32_e32 v64, v68, v68
	v_fmac_f32_e32 v65, v77, v77
	v_add_f32_e32 v64, v64, v65
	v_mul_f32_e32 v65, v92, v92
	v_fmac_f32_e32 v65, v79, v79
	v_add_f32_e32 v64, v65, v64
	v_mul_f32_e32 v65, v94, v94
	v_fmac_f32_e32 v65, v93, v93
	v_add_f32_e32 v64, v65, v64
	v_add_f32_e32 v67, v76, v64
	v_mov_b32_e32 v76, v67
	s_nop 1
	v_permlane16_swap_b32 v67, v76
	v_lshl_add_u64 v[64:65], s[26:27], 0, v[188:189]
	v_lshl_add_u64 v[70:71], v[64:65], 0, v[184:185]
	global_store_dwordx4 v[70:71], v[72:75], off
	v_cvt_pk_bf16_f32 v66, v68, v69
	s_waitcnt lgkmcnt(0)
	v_add_f32_e32 v64, v67, v76
	v_mov_b32_e32 v65, v64
	s_nop 1
	v_permlane32_swap_b32 v64, v65
	v_cvt_pk_bf16_f32 v67, v77, v78
	v_cvt_pk_bf16_f32 v68, v79, v92
	v_cvt_pk_bf16_f32 v69, v93, v94
	global_store_dwordx4 v[70:71], v[66:69], off offset:256
	s_and_saveexec_b64 s[62:63], s[44:45]
	s_cbranch_execz .LBB0_833
	v_lshlrev_b64 v[66:67], 6, v[186:187]
	v_lshl_add_u64 v[66:67], s[28:29], 0, v[66:67]
	v_lshl_add_u64 v[66:67], s[60:61], 2, v[66:67]
	s_lshl_b32 s8, s76, 2
	v_lshl_add_u64 v[66:67], v[66:67], 0, s[8:9]
	s_waitcnt lgkmcnt(0)
	v_add_f32_e32 v64, v64, v65
	flat_store_dword v[66:67], v64
.LBB0_833:
	s_or_b64 exec, exec, s[62:63]
	v_or_b32_e32 v72, 48, v144
	v_ashrrev_i32_e32 v73, 31, v72
	s_waitcnt lgkmcnt(0)
	v_lshlrev_b64 v[64:65], 11, v[72:73]
	v_lshl_add_u64 v[64:65], s[26:27], 0, v[64:65]
	v_lshl_add_u64 v[74:75], v[182:183], 1, v[64:65]
	global_load_dwordx4 v[68:71], v[74:75], off
	global_load_dwordx4 v[64:67], v[74:75], off offset:256
	s_waitcnt vmcnt(15)
	v_lshlrev_b32_e32 v76, 16, v136
	v_add_f32_e32 v60, v60, v76
	v_and_b32_e32 v76, 0xffff0000, v136
	v_add_f32_e32 v61, v61, v76
	v_lshlrev_b32_e32 v76, 16, v137
	v_add_f32_e32 v62, v62, v76
	v_and_b32_e32 v76, 0xffff0000, v137
	v_add_f32_e32 v63, v63, v76
	v_lshlrev_b32_e32 v76, 16, v138
	v_add_f32_e32 v76, v56, v76
	v_and_b32_e32 v56, 0xffff0000, v138
	v_add_f32_e32 v77, v57, v56
	v_lshlrev_b32_e32 v56, 16, v139
	v_add_f32_e32 v78, v58, v56
	v_and_b32_e32 v56, 0xffff0000, v139
	v_mul_f32_e32 v58, v61, v61
	v_add_f32_e32 v59, v59, v56
	v_cvt_pk_bf16_f32 v56, v60, v61
	v_fmac_f32_e32 v58, v60, v60
	v_mul_f32_e32 v60, v63, v63
	v_fmac_f32_e32 v60, v62, v62
	v_add_f32_e32 v58, v58, v60
	v_mul_f32_e32 v60, v77, v77
	v_fmac_f32_e32 v60, v76, v76
	v_add_f32_e32 v58, v60, v58
	v_mul_f32_e32 v60, v59, v59
	v_fmac_f32_e32 v60, v78, v78
	v_add_f32_e32 v58, v60, v58
	v_lshlrev_b32_e32 v60, 16, v128
	v_add_f32_e32 v52, v52, v60
	v_and_b32_e32 v60, 0xffff0000, v128
	v_add_f32_e32 v53, v53, v60
	v_lshlrev_b32_e32 v60, 16, v129
	v_add_f32_e32 v54, v54, v60
	v_and_b32_e32 v60, 0xffff0000, v129
	v_add_f32_e32 v55, v55, v60
	v_lshlrev_b32_e32 v60, 16, v130
	v_add_f32_e32 v60, v48, v60
	v_and_b32_e32 v48, 0xffff0000, v130
	v_add_f32_e32 v61, v49, v48
	v_lshlrev_b32_e32 v48, 16, v131
	v_cvt_pk_bf16_f32 v57, v62, v63
	v_add_f32_e32 v62, v50, v48
	v_and_b32_e32 v48, 0xffff0000, v131
	v_add_f32_e32 v63, v51, v48
	v_mul_f32_e32 v48, v53, v53
	v_mul_f32_e32 v49, v55, v55
	v_fmac_f32_e32 v48, v52, v52
	v_fmac_f32_e32 v49, v54, v54
	v_add_f32_e32 v48, v48, v49
	v_mul_f32_e32 v49, v61, v61
	v_fmac_f32_e32 v49, v60, v60
	v_add_f32_e32 v48, v49, v48
	v_mul_f32_e32 v49, v63, v63
	v_fmac_f32_e32 v49, v62, v62
	v_add_f32_e32 v48, v49, v48
	v_add_f32_e32 v48, v58, v48
	v_mov_b32_e32 v49, v48
	s_nop 1
	v_permlane16_swap_b32 v48, v49
	v_cvt_pk_bf16_f32 v58, v76, v77
	v_cvt_pk_bf16_f32 v59, v78, v59
	global_store_dwordx4 v[146:147], v[56:59], off
	v_cvt_pk_bf16_f32 v50, v52, v53
	s_waitcnt lgkmcnt(0)
	v_add_f32_e32 v48, v48, v49
	v_mov_b32_e32 v49, v48
	s_nop 1
	v_permlane32_swap_b32 v48, v49
	v_cvt_pk_bf16_f32 v51, v54, v55
	v_cvt_pk_bf16_f32 v52, v60, v61
	v_cvt_pk_bf16_f32 v53, v62, v63
	global_store_dwordx4 v[146:147], v[50:53], off offset:256
	s_and_saveexec_b64 s[62:63], s[44:45]
	s_cbranch_execz .LBB0_835
	v_lshlrev_b64 v[50:51], 6, v[144:145]
	v_lshl_add_u64 v[50:51], s[28:29], 0, v[50:51]
	v_lshl_add_u64 v[50:51], s[60:61], 2, v[50:51]
	s_lshl_b32 s8, s76, 2
	v_lshl_add_u64 v[50:51], v[50:51], 0, s[8:9]
	s_waitcnt lgkmcnt(0)
	v_add_f32_e32 v48, v48, v49
	flat_store_dword v[50:51], v48
.LBB0_835:
	s_or_b64 exec, exec, s[62:63]
	s_waitcnt vmcnt(13)
	v_lshlrev_b32_e32 v48, 16, v100
	v_add_f32_e32 v44, v44, v48
	v_and_b32_e32 v48, 0xffff0000, v100
	v_add_f32_e32 v45, v45, v48
	v_lshlrev_b32_e32 v48, 16, v101
	v_add_f32_e32 v46, v46, v48
	v_and_b32_e32 v48, 0xffff0000, v101
	v_add_f32_e32 v47, v47, v48
	v_lshlrev_b32_e32 v48, 16, v102
	v_add_f32_e32 v48, v40, v48
	v_and_b32_e32 v40, 0xffff0000, v102
	s_waitcnt lgkmcnt(0)
	v_add_f32_e32 v49, v41, v40
	v_lshlrev_b32_e32 v40, 16, v103
	v_add_f32_e32 v50, v42, v40
	v_and_b32_e32 v40, 0xffff0000, v103
	v_mul_f32_e32 v42, v45, v45
	v_add_f32_e32 v43, v43, v40
	v_cvt_pk_bf16_f32 v40, v44, v45
	v_fmac_f32_e32 v42, v44, v44
	v_mul_f32_e32 v44, v47, v47
	v_fmac_f32_e32 v44, v46, v46
	v_add_f32_e32 v42, v42, v44
	v_mul_f32_e32 v44, v49, v49
	v_fmac_f32_e32 v44, v48, v48
	v_add_f32_e32 v42, v44, v42
	v_mul_f32_e32 v44, v43, v43
	v_fmac_f32_e32 v44, v50, v50
	v_add_f32_e32 v42, v44, v42
	v_lshlrev_b32_e32 v44, 16, v96
	v_add_f32_e32 v36, v36, v44
	v_and_b32_e32 v44, 0xffff0000, v96
	v_add_f32_e32 v37, v37, v44
	v_lshlrev_b32_e32 v44, 16, v97
	v_add_f32_e32 v38, v38, v44
	v_and_b32_e32 v44, 0xffff0000, v97
	v_add_f32_e32 v39, v39, v44
	v_lshlrev_b32_e32 v44, 16, v98
	v_add_f32_e32 v44, v32, v44
	v_and_b32_e32 v32, 0xffff0000, v98
	v_add_f32_e32 v45, v33, v32
	v_lshlrev_b32_e32 v32, 16, v99
	v_cvt_pk_bf16_f32 v41, v46, v47
	v_add_f32_e32 v46, v34, v32
	v_and_b32_e32 v32, 0xffff0000, v99
	v_add_f32_e32 v47, v35, v32
	v_mul_f32_e32 v32, v37, v37
	v_mul_f32_e32 v33, v39, v39
	v_fmac_f32_e32 v32, v36, v36
	v_fmac_f32_e32 v33, v38, v38
	v_add_f32_e32 v32, v32, v33
	v_mul_f32_e32 v33, v45, v45
	v_fmac_f32_e32 v33, v44, v44
	v_add_f32_e32 v32, v33, v32
	v_mul_f32_e32 v33, v47, v47
	v_fmac_f32_e32 v33, v46, v46
	v_add_f32_e32 v32, v33, v32
	v_add_f32_e32 v32, v42, v32
	v_mov_b32_e32 v33, v32
	s_nop 1
	v_permlane16_swap_b32 v32, v33
	v_cvt_pk_bf16_f32 v42, v48, v49
	v_cvt_pk_bf16_f32 v43, v50, v43
	global_store_dwordx4 v[106:107], v[40:43], off
	v_cvt_pk_bf16_f32 v34, v36, v37
	s_waitcnt lgkmcnt(0)
	v_add_f32_e32 v32, v32, v33
	v_mov_b32_e32 v33, v32
	s_nop 1
	v_permlane32_swap_b32 v32, v33
	v_cvt_pk_bf16_f32 v35, v38, v39
	v_cvt_pk_bf16_f32 v36, v44, v45
	v_cvt_pk_bf16_f32 v37, v46, v47
	global_store_dwordx4 v[106:107], v[34:37], off offset:256
	s_and_saveexec_b64 s[62:63], s[44:45]
	s_cbranch_execz .LBB0_837
	v_lshlrev_b64 v[34:35], 6, v[104:105]
	v_lshl_add_u64 v[34:35], s[28:29], 0, v[34:35]
	v_lshl_add_u64 v[34:35], s[60:61], 2, v[34:35]
	s_lshl_b32 s8, s76, 2
	v_lshl_add_u64 v[34:35], v[34:35], 0, s[8:9]
	s_waitcnt lgkmcnt(0)
	v_add_f32_e32 v32, v32, v33
	flat_store_dword v[34:35], v32
.LBB0_837:
	s_or_b64 exec, exec, s[62:63]
	s_waitcnt vmcnt(11)
	v_lshlrev_b32_e32 v32, 16, v84
	v_add_f32_e32 v28, v28, v32
	v_and_b32_e32 v32, 0xffff0000, v84
	v_add_f32_e32 v29, v29, v32
	v_lshlrev_b32_e32 v32, 16, v85
	v_add_f32_e32 v30, v30, v32
	v_and_b32_e32 v32, 0xffff0000, v85
	v_add_f32_e32 v31, v31, v32
	v_lshlrev_b32_e32 v32, 16, v86
	v_add_f32_e32 v32, v24, v32
	v_and_b32_e32 v24, 0xffff0000, v86
	s_waitcnt lgkmcnt(0)
	v_add_f32_e32 v33, v25, v24
	v_lshlrev_b32_e32 v24, 16, v87
	v_add_f32_e32 v34, v26, v24
	v_and_b32_e32 v24, 0xffff0000, v87
	v_mul_f32_e32 v26, v29, v29
	v_add_f32_e32 v27, v27, v24
	v_cvt_pk_bf16_f32 v24, v28, v29
	v_fmac_f32_e32 v26, v28, v28
	v_mul_f32_e32 v28, v31, v31
	v_fmac_f32_e32 v28, v30, v30
	v_add_f32_e32 v26, v26, v28
	v_mul_f32_e32 v28, v33, v33
	v_fmac_f32_e32 v28, v32, v32
	v_add_f32_e32 v26, v28, v26
	v_mul_f32_e32 v28, v27, v27
	v_fmac_f32_e32 v28, v34, v34
	v_add_f32_e32 v26, v28, v26
	v_lshlrev_b32_e32 v28, 16, v80
	v_add_f32_e32 v20, v20, v28
	v_and_b32_e32 v28, 0xffff0000, v80
	v_add_f32_e32 v21, v21, v28
	v_lshlrev_b32_e32 v28, 16, v81
	v_add_f32_e32 v22, v22, v28
	v_and_b32_e32 v28, 0xffff0000, v81
	v_add_f32_e32 v23, v23, v28
	v_lshlrev_b32_e32 v28, 16, v82
	v_add_f32_e32 v28, v16, v28
	v_and_b32_e32 v16, 0xffff0000, v82
	v_add_f32_e32 v29, v17, v16
	v_lshlrev_b32_e32 v16, 16, v83
	v_cvt_pk_bf16_f32 v25, v30, v31
	v_add_f32_e32 v30, v18, v16
	v_and_b32_e32 v16, 0xffff0000, v83
	v_add_f32_e32 v31, v19, v16
	v_mul_f32_e32 v16, v21, v21
	v_mul_f32_e32 v17, v23, v23
	v_fmac_f32_e32 v16, v20, v20
	v_fmac_f32_e32 v17, v22, v22
	v_add_f32_e32 v16, v16, v17
	v_mul_f32_e32 v17, v29, v29
	v_fmac_f32_e32 v17, v28, v28
	v_add_f32_e32 v16, v17, v16
	v_mul_f32_e32 v17, v31, v31
	v_fmac_f32_e32 v17, v30, v30
	v_add_f32_e32 v16, v17, v16
	v_add_f32_e32 v16, v26, v16
	v_mov_b32_e32 v17, v16
	s_nop 1
	v_permlane16_swap_b32 v16, v17
	v_cvt_pk_bf16_f32 v26, v32, v33
	v_cvt_pk_bf16_f32 v27, v34, v27
	global_store_dwordx4 v[90:91], v[24:27], off
	v_cvt_pk_bf16_f32 v18, v20, v21
	s_waitcnt lgkmcnt(0)
	v_add_f32_e32 v16, v16, v17
	v_mov_b32_e32 v17, v16
	s_nop 1
	v_permlane32_swap_b32 v16, v17
	v_cvt_pk_bf16_f32 v19, v22, v23
	v_cvt_pk_bf16_f32 v20, v28, v29
	v_cvt_pk_bf16_f32 v21, v30, v31
	global_store_dwordx4 v[90:91], v[18:21], off offset:256
	s_and_saveexec_b64 s[62:63], s[44:45]
	s_cbranch_execz .LBB0_839
	v_lshlrev_b64 v[18:19], 6, v[88:89]
	v_lshl_add_u64 v[18:19], s[28:29], 0, v[18:19]
	v_lshl_add_u64 v[18:19], s[60:61], 2, v[18:19]
	s_lshl_b32 s8, s76, 2
	v_lshl_add_u64 v[18:19], v[18:19], 0, s[8:9]
	s_waitcnt lgkmcnt(0)
	v_add_f32_e32 v16, v16, v17
	flat_store_dword v[18:19], v16
.LBB0_839:
	s_or_b64 exec, exec, s[62:63]
	s_waitcnt vmcnt(9)
	v_lshlrev_b32_e32 v16, 16, v68
	v_add_f32_e32 v12, v12, v16
	v_and_b32_e32 v16, 0xffff0000, v68
	v_add_f32_e32 v13, v13, v16
	v_lshlrev_b32_e32 v16, 16, v69
	v_add_f32_e32 v14, v14, v16
	v_and_b32_e32 v16, 0xffff0000, v69
	v_add_f32_e32 v15, v15, v16
	v_lshlrev_b32_e32 v16, 16, v70
	v_add_f32_e32 v16, v8, v16
	v_and_b32_e32 v8, 0xffff0000, v70
	s_waitcnt lgkmcnt(0)
	v_add_f32_e32 v17, v9, v8
	v_lshlrev_b32_e32 v8, 16, v71
	v_add_f32_e32 v18, v10, v8
	v_and_b32_e32 v8, 0xffff0000, v71
	v_mul_f32_e32 v10, v13, v13
	v_add_f32_e32 v11, v11, v8
	v_cvt_pk_bf16_f32 v8, v12, v13
	v_fmac_f32_e32 v10, v12, v12
	v_mul_f32_e32 v12, v15, v15
	v_fmac_f32_e32 v12, v14, v14
	v_add_f32_e32 v10, v10, v12
	v_mul_f32_e32 v12, v17, v17
	v_fmac_f32_e32 v12, v16, v16
	v_add_f32_e32 v10, v12, v10
	v_mul_f32_e32 v12, v11, v11
	v_fmac_f32_e32 v12, v18, v18
	v_add_f32_e32 v10, v12, v10
	v_lshlrev_b32_e32 v12, 16, v64
	v_add_f32_e32 v4, v4, v12
	v_and_b32_e32 v12, 0xffff0000, v64
	v_add_f32_e32 v5, v5, v12
	v_lshlrev_b32_e32 v12, 16, v65
	v_add_f32_e32 v6, v6, v12
	v_and_b32_e32 v12, 0xffff0000, v65
	v_add_f32_e32 v7, v7, v12
	v_lshlrev_b32_e32 v12, 16, v66
	v_add_f32_e32 v12, v0, v12
	v_and_b32_e32 v0, 0xffff0000, v66
	v_add_f32_e32 v13, v1, v0
	v_lshlrev_b32_e32 v0, 16, v67
	v_cvt_pk_bf16_f32 v9, v14, v15
	v_add_f32_e32 v14, v2, v0
	v_and_b32_e32 v0, 0xffff0000, v67
	v_add_f32_e32 v15, v3, v0
	v_mul_f32_e32 v0, v5, v5
	v_mul_f32_e32 v1, v7, v7
	v_fmac_f32_e32 v0, v4, v4
	v_fmac_f32_e32 v1, v6, v6
	v_add_f32_e32 v0, v0, v1
	v_mul_f32_e32 v1, v13, v13
	v_fmac_f32_e32 v1, v12, v12
	v_add_f32_e32 v0, v1, v0
	v_mul_f32_e32 v1, v15, v15
	v_fmac_f32_e32 v1, v14, v14
	v_add_f32_e32 v0, v1, v0
	v_add_f32_e32 v0, v10, v0
	v_mov_b32_e32 v1, v0
	s_nop 1
	v_permlane16_swap_b32 v0, v1
	v_cvt_pk_bf16_f32 v10, v16, v17
	v_cvt_pk_bf16_f32 v11, v18, v11
	global_store_dwordx4 v[74:75], v[8:11], off
	v_cvt_pk_bf16_f32 v2, v4, v5
	s_waitcnt lgkmcnt(0)
	v_add_f32_e32 v0, v0, v1
	v_mov_b32_e32 v1, v0
	s_nop 1
	v_permlane32_swap_b32 v0, v1
	v_cvt_pk_bf16_f32 v3, v6, v7
	v_cvt_pk_bf16_f32 v4, v12, v13
	v_cvt_pk_bf16_f32 v5, v14, v15
	global_store_dwordx4 v[74:75], v[2:5], off offset:256
	s_and_saveexec_b64 s[62:63], s[44:45]
	s_cbranch_execz .LBB0_841
	v_lshlrev_b64 v[2:3], 6, v[72:73]
	v_lshl_add_u64 v[2:3], s[28:29], 0, v[2:3]
	v_lshl_add_u64 v[2:3], s[60:61], 2, v[2:3]
	s_lshl_b32 s8, s76, 2
	v_lshl_add_u64 v[2:3], v[2:3], 0, s[8:9]
	s_waitcnt lgkmcnt(0)
	v_add_f32_e32 v0, v0, v1
	flat_store_dword v[2:3], v0
